# v12 + snake order of the MFMAs inside each 8-group (one operand changes per step)
# baseline (speedup 1.0000x reference)
.LBB0_224:
	ds_read_b128 v[46:49], v196
	ds_read_b128 v[50:53], v196 offset:1024
	ds_read_b128 v[66:69], v196 offset:2048
	ds_read_b128 v[70:73], v196 offset:3072
	ds_read_b128 v[164:167], v197
	ds_read_b128 v[168:171], v197 offset:1024
	ds_read_b128 v[172:175], v197 offset:2048
	ds_read_b128 v[176:179], v197 offset:3072
	s_add_u32 s30, s28, 0xfff80080
	s_addc_u32 s31, s29, -1
	s_cmp_eq_u32 s38, 28
	s_cselect_b32 s35, s5, s31
	s_cselect_b32 s34, s7, s30
	s_cselect_b32 s31, s21, s37
	s_cselect_b32 s30, s23, s36
	s_add_i32 m0, s17, 0xc000
	ds_read_b128 v[184:187], v198
	ds_read_b128 v[188:191], v198 offset:1024
	ds_read_b128 v[200:203], v198 offset:2048
	ds_read_b128 v[204:207], v198 offset:3072
	ds_read_b128 v[208:211], v198 offset:4096
	ds_read_b128 v[212:215], v198 offset:5120
	ds_read_b128 v[216:219], v198 offset:6144
	ds_read_b128 v[220:223], v198 offset:7168
	global_load_lds_dwordx4 v156, s[28:29]
	s_add_i32 m0, s17, 0xe000
	s_nop 0
	global_load_lds_dwordx4 v158, s[28:29]
	s_waitcnt vmcnt(8)
	s_waitcnt lgkmcnt(0)
	s_barrier
	s_setprio 1
	s_waitcnt lgkmcnt(0)
	v_mfma_i32_16x16x64_i8 v[142:145], v[46:49], v[184:187], v[142:145]
	v_mfma_i32_16x16x64_i8 v[138:141], v[66:69], v[184:187], v[138:141]
	v_mfma_i32_16x16x64_i8 v[130:133], v[66:69], v[200:203], v[130:133]
	v_mfma_i32_16x16x64_i8 v[134:137], v[46:49], v[200:203], v[134:137]
	v_mfma_i32_16x16x64_i8 v[118:121], v[46:49], v[208:211], v[118:121]
	v_mfma_i32_16x16x64_i8 v[114:117], v[66:69], v[208:211], v[114:117]
	v_mfma_i32_16x16x64_i8 v[98:101], v[66:69], v[216:219], v[98:101]
	v_mfma_i32_16x16x64_i8 v[102:105], v[46:49], v[216:219], v[102:105]
	v_mfma_i32_16x16x64_i8 v[142:145], v[50:53], v[188:191], v[142:145]
	v_mfma_i32_16x16x64_i8 v[138:141], v[70:73], v[188:191], v[138:141]
	v_mfma_i32_16x16x64_i8 v[130:133], v[70:73], v[204:207], v[130:133]
	v_mfma_i32_16x16x64_i8 v[134:137], v[50:53], v[204:207], v[134:137]
	v_mfma_i32_16x16x64_i8 v[118:121], v[50:53], v[212:215], v[118:121]
	v_mfma_i32_16x16x64_i8 v[114:117], v[70:73], v[212:215], v[114:117]
	v_mfma_i32_16x16x64_i8 v[98:101], v[70:73], v[220:223], v[98:101]
	v_mfma_i32_16x16x64_i8 v[102:105], v[50:53], v[220:223], v[102:105]
	s_setprio 0
	s_setprio 1
	v_mfma_i32_16x16x64_i8 v[126:129], v[164:167], v[184:187], v[126:129]
	v_mfma_i32_16x16x64_i8 v[122:125], v[172:175], v[184:187], v[122:125]
	v_mfma_i32_16x16x64_i8 v[106:109], v[172:175], v[200:203], v[106:109]
	v_mfma_i32_16x16x64_i8 v[110:113], v[164:167], v[200:203], v[110:113]
	v_mfma_i32_16x16x64_i8 v[94:97], v[164:167], v[208:211], v[94:97]
	v_mfma_i32_16x16x64_i8 v[90:93], v[172:175], v[208:211], v[90:93]
	v_mfma_i32_16x16x64_i8 v[82:85], v[172:175], v[216:219], v[82:85]
	v_mfma_i32_16x16x64_i8 v[86:89], v[164:167], v[216:219], v[86:89]
	v_mfma_i32_16x16x64_i8 v[126:129], v[168:171], v[188:191], v[126:129]
	v_mfma_i32_16x16x64_i8 v[122:125], v[176:179], v[188:191], v[122:125]
	v_mfma_i32_16x16x64_i8 v[106:109], v[176:179], v[204:207], v[106:109]
	v_mfma_i32_16x16x64_i8 v[110:113], v[168:171], v[204:207], v[110:113]
	v_mfma_i32_16x16x64_i8 v[94:97], v[168:171], v[212:215], v[94:97]
	v_mfma_i32_16x16x64_i8 v[90:93], v[176:179], v[212:215], v[90:93]
	v_mfma_i32_16x16x64_i8 v[82:85], v[176:179], v[220:223], v[82:85]
	v_mfma_i32_16x16x64_i8 v[86:89], v[168:171], v[220:223], v[86:89]
	s_setprio 0
	s_barrier
	s_add_i32 s39, s76, s9
	s_mov_b32 m0, s39
	ds_read_b128 v[184:187], v198 offset:16384
	ds_read_b128 v[188:191], v198 offset:17408
	ds_read_b128 v[200:203], v198 offset:18432
	ds_read_b128 v[204:207], v198 offset:19456
	ds_read_b128 v[208:211], v198 offset:20480
	ds_read_b128 v[212:215], v198 offset:21504
	ds_read_b128 v[216:219], v198 offset:22528
	ds_read_b128 v[220:223], v198 offset:23552
	global_load_lds_dwordx4 v146, s[30:31]
	s_add_i32 m0, s39, 0x2000
	s_add_u32 s46, s30, 0x80000
	s_addc_u32 s47, s31, 0
	s_add_i32 s39, s77, s9
	global_load_lds_dwordx4 v148, s[30:31]
	s_mov_b32 m0, s39
	s_nop 0
	global_load_lds_dwordx4 v146, s[46:47]
	s_add_i32 m0, s39, 0x2000
	s_nop 0
	global_load_lds_dwordx4 v148, s[46:47]
	s_mov_b32 m0, s17
	s_nop 0
	global_load_lds_dwordx4 v146, s[34:35]
	s_mov_b32 m0, s40
	s_nop 0
	global_load_lds_dwordx4 v148, s[34:35]
	s_waitcnt vmcnt(8)
	s_waitcnt lgkmcnt(0)
	s_barrier
	s_setprio 1
	s_waitcnt lgkmcnt(0)
	v_mfma_i32_16x16x64_i8 v[78:81], v[46:49], v[184:187], v[78:81]
	v_mfma_i32_16x16x64_i8 v[74:77], v[66:69], v[184:187], v[74:77]
	v_mfma_i32_16x16x64_i8 v[42:45], v[66:69], v[200:203], v[42:45]
	v_mfma_i32_16x16x64_i8 v[54:57], v[46:49], v[200:203], v[54:57]
	v_mfma_i32_16x16x64_i8 v[30:33], v[46:49], v[208:211], v[30:33]
	v_mfma_i32_16x16x64_i8 v[26:29], v[66:69], v[208:211], v[26:29]
	v_mfma_i32_16x16x64_i8 v[10:13], v[66:69], v[216:219], v[10:13]
	v_mfma_i32_16x16x64_i8 v[14:17], v[46:49], v[216:219], v[14:17]
	v_mfma_i32_16x16x64_i8 v[78:81], v[50:53], v[188:191], v[78:81]
	v_mfma_i32_16x16x64_i8 v[74:77], v[70:73], v[188:191], v[74:77]
	v_mfma_i32_16x16x64_i8 v[42:45], v[70:73], v[204:207], v[42:45]
	v_mfma_i32_16x16x64_i8 v[54:57], v[50:53], v[204:207], v[54:57]
	v_mfma_i32_16x16x64_i8 v[30:33], v[50:53], v[212:215], v[30:33]
	v_mfma_i32_16x16x64_i8 v[26:29], v[70:73], v[212:215], v[26:29]
	v_mfma_i32_16x16x64_i8 v[10:13], v[70:73], v[220:223], v[10:13]
	v_mfma_i32_16x16x64_i8 v[14:17], v[50:53], v[220:223], v[14:17]
	s_setprio 0
	s_setprio 1
	v_mfma_i32_16x16x64_i8 v[38:41], v[164:167], v[200:203], v[38:41]
	v_mfma_i32_16x16x64_i8 v[34:37], v[172:175], v[200:203], v[34:37]
	v_mfma_i32_16x16x64_i8 v[18:21], v[172:175], v[208:211], v[18:21]
	v_mfma_i32_16x16x64_i8 v[22:25], v[164:167], v[208:211], v[22:25]
	v_mfma_i32_16x16x64_i8 v[6:9], v[164:167], v[216:219], v[6:9]
	v_mfma_i32_16x16x64_i8 v[2:5], v[172:175], v[216:219], v[2:5]
	v_mfma_i32_16x16x64_i8 v[50:53], v[172:175], v[184:187], v[58:61]
	v_mfma_i32_16x16x64_i8 v[46:49], v[164:167], v[184:187], v[62:65]
	v_mfma_i32_16x16x64_i8 v[38:41], v[168:171], v[204:207], v[38:41]
	v_mfma_i32_16x16x64_i8 v[34:37], v[176:179], v[204:207], v[34:37]
	v_mfma_i32_16x16x64_i8 v[18:21], v[176:179], v[212:215], v[18:21]
	v_mfma_i32_16x16x64_i8 v[22:25], v[168:171], v[212:215], v[22:25]
	v_mfma_i32_16x16x64_i8 v[6:9], v[168:171], v[220:223], v[6:9]
	v_mfma_i32_16x16x64_i8 v[2:5], v[176:179], v[220:223], v[2:5]
	v_mfma_i32_16x16x64_i8 v[50:53], v[176:179], v[188:191], v[50:53]
	v_mfma_i32_16x16x64_i8 v[46:49], v[168:171], v[188:191], v[46:49]
	s_setprio 0
	s_barrier
	s_add_i32 s39, 0, 0x18000
	v_add_u32_e32 v1, s39, v194
	s_add_i32 s46, 0, 0x1c000
	ds_read_b128 v[58:61], v1
	ds_read_b128 v[62:65], v1 offset:1024
	ds_read_b128 v[66:69], v1 offset:2048
	ds_read_b128 v[70:73], v1 offset:3072
	v_add_u32_e32 v1, s46, v194
	ds_read_b128 v[164:167], v1
	ds_read_b128 v[168:171], v1 offset:1024
	ds_read_b128 v[172:175], v1 offset:2048
	ds_read_b128 v[176:179], v1 offset:3072
	s_add_u32 s34, s34, 0x80000
	s_addc_u32 s35, s35, 0
	s_mov_b32 m0, s41
	ds_read_b128 v[184:187], v198 offset:32768
	ds_read_b128 v[188:191], v198 offset:33792
	ds_read_b128 v[200:203], v198 offset:34816
	ds_read_b128 v[204:207], v198 offset:35840
	ds_read_b128 v[208:211], v198 offset:36864
	ds_read_b128 v[212:215], v198 offset:37888
	ds_read_b128 v[216:219], v198 offset:38912
	ds_read_b128 v[220:223], v198 offset:39936
	global_load_lds_dwordx4 v146, s[34:35]
	s_mov_b32 m0, s42
	s_nop 0
	global_load_lds_dwordx4 v148, s[34:35]
	s_waitcnt vmcnt(8)
	s_waitcnt lgkmcnt(0)
	s_barrier
	s_setprio 1
	s_waitcnt lgkmcnt(0)
	v_mfma_i32_16x16x64_i8 v[142:145], v[58:61], v[184:187], v[142:145]
	v_mfma_i32_16x16x64_i8 v[138:141], v[66:69], v[184:187], v[138:141]
	v_mfma_i32_16x16x64_i8 v[130:133], v[66:69], v[200:203], v[130:133]
	v_mfma_i32_16x16x64_i8 v[134:137], v[58:61], v[200:203], v[134:137]
	v_mfma_i32_16x16x64_i8 v[118:121], v[58:61], v[208:211], v[118:121]
	v_mfma_i32_16x16x64_i8 v[114:117], v[66:69], v[208:211], v[114:117]
	v_mfma_i32_16x16x64_i8 v[98:101], v[66:69], v[216:219], v[98:101]
	v_mfma_i32_16x16x64_i8 v[102:105], v[58:61], v[216:219], v[102:105]
	v_mfma_i32_16x16x64_i8 v[142:145], v[62:65], v[188:191], v[142:145]
	v_mfma_i32_16x16x64_i8 v[138:141], v[70:73], v[188:191], v[138:141]
	v_mfma_i32_16x16x64_i8 v[130:133], v[70:73], v[204:207], v[130:133]
	v_mfma_i32_16x16x64_i8 v[134:137], v[62:65], v[204:207], v[134:137]
	v_mfma_i32_16x16x64_i8 v[118:121], v[62:65], v[212:215], v[118:121]
	v_mfma_i32_16x16x64_i8 v[114:117], v[70:73], v[212:215], v[114:117]
	v_mfma_i32_16x16x64_i8 v[98:101], v[70:73], v[220:223], v[98:101]
	v_mfma_i32_16x16x64_i8 v[102:105], v[62:65], v[220:223], v[102:105]
	s_setprio 0
	s_setprio 1
	v_mfma_i32_16x16x64_i8 v[126:129], v[164:167], v[184:187], v[126:129]
	v_mfma_i32_16x16x64_i8 v[122:125], v[172:175], v[184:187], v[122:125]
	v_mfma_i32_16x16x64_i8 v[106:109], v[172:175], v[200:203], v[106:109]
	v_mfma_i32_16x16x64_i8 v[110:113], v[164:167], v[200:203], v[110:113]
	v_mfma_i32_16x16x64_i8 v[94:97], v[164:167], v[208:211], v[94:97]
	v_mfma_i32_16x16x64_i8 v[90:93], v[172:175], v[208:211], v[90:93]
	v_mfma_i32_16x16x64_i8 v[82:85], v[172:175], v[216:219], v[82:85]
	v_mfma_i32_16x16x64_i8 v[86:89], v[164:167], v[216:219], v[86:89]
	v_mfma_i32_16x16x64_i8 v[126:129], v[168:171], v[188:191], v[126:129]
	v_mfma_i32_16x16x64_i8 v[122:125], v[176:179], v[188:191], v[122:125]
	v_mfma_i32_16x16x64_i8 v[106:109], v[176:179], v[204:207], v[106:109]
	v_mfma_i32_16x16x64_i8 v[110:113], v[168:171], v[204:207], v[110:113]
	v_mfma_i32_16x16x64_i8 v[94:97], v[168:171], v[212:215], v[94:97]
	v_mfma_i32_16x16x64_i8 v[90:93], v[176:179], v[212:215], v[90:93]
	v_mfma_i32_16x16x64_i8 v[82:85], v[176:179], v[220:223], v[82:85]
	v_mfma_i32_16x16x64_i8 v[86:89], v[168:171], v[220:223], v[86:89]
	s_setprio 0
	s_barrier
	s_add_u32 s98, s34, 0xfff80080
	s_addc_u32 s99, s35, -1
	s_add_i32 s34, s39, s9
	s_mov_b32 m0, s34
	ds_read_b128 v[184:187], v198 offset:49152
	ds_read_b128 v[188:191], v198 offset:50176
	ds_read_b128 v[200:203], v198 offset:51200
	ds_read_b128 v[204:207], v198 offset:52224
	ds_read_b128 v[208:211], v198 offset:53248
	ds_read_b128 v[212:215], v198 offset:54272
	ds_read_b128 v[216:219], v198 offset:55296
	ds_read_b128 v[220:223], v198 offset:56320
	s_add_u32 s100, s30, 0x80
	s_addc_u32 s101, s31, 0
	global_load_lds_dwordx4 v146, s[100:101]
	s_add_i32 m0, s34, 0x2000
	s_add_u32 s30, s30, 0x80080
	s_addc_u32 s31, s31, 0
	s_add_i32 s34, s46, s9
	global_load_lds_dwordx4 v148, s[100:101]
	s_mov_b32 m0, s34
	s_nop 0
	global_load_lds_dwordx4 v146, s[30:31]
	s_add_i32 m0, s34, 0x2000
	s_nop 0
	global_load_lds_dwordx4 v148, s[30:31]
	s_mov_b32 m0, s72
	s_nop 0
	global_load_lds_dwordx4 v146, s[98:99]
	s_mov_b32 m0, s73
	s_nop 0
	global_load_lds_dwordx4 v148, s[98:99]
	s_waitcnt vmcnt(8)
	s_waitcnt lgkmcnt(0)
	s_barrier
	s_setprio 1
	s_waitcnt lgkmcnt(0)
	v_mfma_i32_16x16x64_i8 v[78:81], v[58:61], v[184:187], v[78:81]
	v_mfma_i32_16x16x64_i8 v[74:77], v[66:69], v[184:187], v[74:77]
	v_mfma_i32_16x16x64_i8 v[42:45], v[66:69], v[200:203], v[42:45]
	v_mfma_i32_16x16x64_i8 v[54:57], v[58:61], v[200:203], v[54:57]
	v_mfma_i32_16x16x64_i8 v[30:33], v[58:61], v[208:211], v[30:33]
	v_mfma_i32_16x16x64_i8 v[26:29], v[66:69], v[208:211], v[26:29]
	v_mfma_i32_16x16x64_i8 v[10:13], v[66:69], v[216:219], v[10:13]
	v_mfma_i32_16x16x64_i8 v[14:17], v[58:61], v[216:219], v[14:17]
	v_mfma_i32_16x16x64_i8 v[78:81], v[62:65], v[188:191], v[78:81]
	v_mfma_i32_16x16x64_i8 v[74:77], v[70:73], v[188:191], v[74:77]
	v_mfma_i32_16x16x64_i8 v[42:45], v[70:73], v[204:207], v[42:45]
	v_mfma_i32_16x16x64_i8 v[54:57], v[62:65], v[204:207], v[54:57]
	v_mfma_i32_16x16x64_i8 v[30:33], v[62:65], v[212:215], v[30:33]
	v_mfma_i32_16x16x64_i8 v[26:29], v[70:73], v[212:215], v[26:29]
	v_mfma_i32_16x16x64_i8 v[10:13], v[70:73], v[220:223], v[10:13]
	v_mfma_i32_16x16x64_i8 v[14:17], v[62:65], v[220:223], v[14:17]
	s_setprio 0
	s_setprio 1
	v_mfma_i32_16x16x64_i8 v[46:49], v[164:167], v[184:187], v[46:49]
	v_mfma_i32_16x16x64_i8 v[62:65], v[168:171], v[188:191], v[46:49]
	v_mfma_i32_16x16x64_i8 v[46:49], v[172:175], v[184:187], v[50:53]
	v_mfma_i32_16x16x64_i8 v[38:41], v[164:167], v[200:203], v[38:41]
	v_mfma_i32_16x16x64_i8 v[34:37], v[172:175], v[200:203], v[34:37]
	v_mfma_i32_16x16x64_i8 v[22:25], v[164:167], v[208:211], v[22:25]
	v_mfma_i32_16x16x64_i8 v[18:21], v[172:175], v[208:211], v[18:21]
	v_mfma_i32_16x16x64_i8 v[6:9], v[164:167], v[216:219], v[6:9]
	v_mfma_i32_16x16x64_i8 v[2:5], v[172:175], v[216:219], v[2:5]
	v_mfma_i32_16x16x64_i8 v[58:61], v[176:179], v[188:191], v[46:49]
	v_mfma_i32_16x16x64_i8 v[38:41], v[168:171], v[204:207], v[38:41]
	v_mfma_i32_16x16x64_i8 v[34:37], v[176:179], v[204:207], v[34:37]
	v_mfma_i32_16x16x64_i8 v[22:25], v[168:171], v[212:215], v[22:25]
	v_mfma_i32_16x16x64_i8 v[18:21], v[176:179], v[212:215], v[18:21]
	v_mfma_i32_16x16x64_i8 v[6:9], v[168:171], v[220:223], v[6:9]
	v_mfma_i32_16x16x64_i8 v[2:5], v[176:179], v[220:223], v[2:5]
	s_setprio 0
	s_barrier
	s_add_i32 s38, s38, 2
	s_add_u32 s28, s28, 0x100
	s_addc_u32 s29, s29, 0
	s_add_u32 s36, s36, 0x100
	s_addc_u32 s37, s37, 0
	s_cmp_gt_u32 s38, 29
	s_cbranch_scc0 .LBB0_224
	s_and_b64 vcc, exec, s[14:15]
	s_cbranch_vccz .LBB0_227
	s_barrier

.LBB0_550:
	ds_read_b128 v[106:109], v147
	ds_read_b128 v[110:113], v147 offset:1024
	ds_read_b128 v[114:117], v147 offset:2048
	ds_read_b128 v[118:121], v147 offset:3072
	ds_read_b128 v[174:177], v197
	ds_read_b128 v[200:203], v197 offset:1024
	ds_read_b128 v[204:207], v197 offset:2048
	ds_read_b128 v[208:211], v197 offset:3072
	s_add_u32 s36, s34, 0xfffc0080
	s_addc_u32 s37, s35, -1
	s_cmp_eq_u32 s74, 12
	s_cselect_b32 s39, s25, s37
	s_cselect_b32 s38, s70, s36
	s_cselect_b32 s37, s23, s73
	s_cselect_b32 s36, s71, s72
	s_add_i32 m0, s31, 0xc000
	ds_read_b128 v[212:215], v198
	ds_read_b128 v[216:219], v198 offset:1024
	ds_read_b128 v[220:223], v198 offset:2048
	ds_read_b128 v[224:227], v198 offset:3072
	ds_read_b128 v[228:231], v198 offset:4096
	ds_read_b128 v[232:235], v198 offset:5120
	ds_read_b128 v[236:239], v198 offset:6144
	ds_read_b128 v[240:243], v198 offset:7168
	global_load_lds_dwordx4 v154, s[34:35]
	s_add_i32 m0, s31, 0xe000
	s_nop 0
	global_load_lds_dwordx4 v156, s[34:35]
	s_waitcnt vmcnt(8)
	s_waitcnt lgkmcnt(0)
	s_barrier
	s_setprio 1
	s_waitcnt lgkmcnt(0)
	v_mfma_i32_16x16x64_i8 v[142:145], v[106:109], v[212:215], v[142:145]
	v_mfma_i32_16x16x64_i8 v[138:141], v[114:117], v[212:215], v[138:141]
	v_mfma_i32_16x16x64_i8 v[122:125], v[114:117], v[220:223], v[122:125]
	v_mfma_i32_16x16x64_i8 v[126:129], v[106:109], v[220:223], v[126:129]
	v_mfma_i32_16x16x64_i8 v[94:97], v[106:109], v[228:231], v[94:97]
	v_mfma_i32_16x16x64_i8 v[90:93], v[114:117], v[228:231], v[90:93]
	v_mfma_i32_16x16x64_i8 v[74:77], v[114:117], v[236:239], v[74:77]
	v_mfma_i32_16x16x64_i8 v[78:81], v[106:109], v[236:239], v[78:81]
	v_mfma_i32_16x16x64_i8 v[142:145], v[110:113], v[216:219], v[142:145]
	v_mfma_i32_16x16x64_i8 v[138:141], v[118:121], v[216:219], v[138:141]
	v_mfma_i32_16x16x64_i8 v[122:125], v[118:121], v[224:227], v[122:125]
	v_mfma_i32_16x16x64_i8 v[126:129], v[110:113], v[224:227], v[126:129]
	v_mfma_i32_16x16x64_i8 v[94:97], v[110:113], v[232:235], v[94:97]
	v_mfma_i32_16x16x64_i8 v[90:93], v[118:121], v[232:235], v[90:93]
	v_mfma_i32_16x16x64_i8 v[74:77], v[118:121], v[240:243], v[74:77]
	v_mfma_i32_16x16x64_i8 v[78:81], v[110:113], v[240:243], v[78:81]
	s_setprio 0
	s_setprio 1
	v_mfma_i32_16x16x64_i8 v[134:137], v[174:177], v[212:215], v[134:137]
	v_mfma_i32_16x16x64_i8 v[130:133], v[204:207], v[212:215], v[130:133]
	v_mfma_i32_16x16x64_i8 v[98:101], v[204:207], v[220:223], v[98:101]
	v_mfma_i32_16x16x64_i8 v[102:105], v[174:177], v[220:223], v[102:105]
	v_mfma_i32_16x16x64_i8 v[86:89], v[174:177], v[228:231], v[86:89]
	v_mfma_i32_16x16x64_i8 v[82:85], v[204:207], v[228:231], v[82:85]
	v_mfma_i32_16x16x64_i8 v[66:69], v[204:207], v[236:239], v[66:69]
	v_mfma_i32_16x16x64_i8 v[70:73], v[174:177], v[236:239], v[70:73]
	v_mfma_i32_16x16x64_i8 v[134:137], v[200:203], v[216:219], v[134:137]
	v_mfma_i32_16x16x64_i8 v[130:133], v[208:211], v[216:219], v[130:133]
	v_mfma_i32_16x16x64_i8 v[98:101], v[208:211], v[224:227], v[98:101]
	v_mfma_i32_16x16x64_i8 v[102:105], v[200:203], v[224:227], v[102:105]
	v_mfma_i32_16x16x64_i8 v[86:89], v[200:203], v[232:235], v[86:89]
	v_mfma_i32_16x16x64_i8 v[82:85], v[208:211], v[232:235], v[82:85]
	v_mfma_i32_16x16x64_i8 v[66:69], v[208:211], v[240:243], v[66:69]
	v_mfma_i32_16x16x64_i8 v[70:73], v[200:203], v[240:243], v[70:73]
	s_setprio 0
	s_barrier
	s_add_i32 s75, s67, s41
	s_mov_b32 m0, s75
	ds_read_b128 v[212:215], v198 offset:16384
	ds_read_b128 v[216:219], v198 offset:17408
	ds_read_b128 v[220:223], v198 offset:18432
	ds_read_b128 v[224:227], v198 offset:19456
	ds_read_b128 v[228:231], v198 offset:20480
	ds_read_b128 v[232:235], v198 offset:21504
	ds_read_b128 v[236:239], v198 offset:22528
	ds_read_b128 v[240:243], v198 offset:23552
	global_load_lds_dwordx4 v148, s[36:37]
	s_add_i32 m0, s75, 0x2000
	s_add_u32 s76, s36, 0x40000
	s_addc_u32 s77, s37, 0
	s_add_i32 s75, s68, s41
	global_load_lds_dwordx4 v150, s[36:37]
	s_mov_b32 m0, s75
	s_nop 0
	global_load_lds_dwordx4 v148, s[76:77]
	s_add_i32 m0, s75, 0x2000
	s_nop 0
	global_load_lds_dwordx4 v150, s[76:77]
	s_mov_b32 m0, s31
	s_nop 0
	global_load_lds_dwordx4 v148, s[38:39]
	s_mov_b32 m0, s42
	s_nop 0
	global_load_lds_dwordx4 v150, s[38:39]
	s_waitcnt vmcnt(8)
	s_waitcnt lgkmcnt(0)
	s_barrier
	s_setprio 1
	s_waitcnt lgkmcnt(0)
	v_mfma_i32_16x16x64_i8 v[62:65], v[106:109], v[212:215], v[62:65]
	v_mfma_i32_16x16x64_i8 v[58:61], v[114:117], v[212:215], v[58:61]
	v_mfma_i32_16x16x64_i8 v[42:45], v[114:117], v[220:223], v[42:45]
	v_mfma_i32_16x16x64_i8 v[46:49], v[106:109], v[220:223], v[46:49]
	v_mfma_i32_16x16x64_i8 v[30:33], v[106:109], v[228:231], v[30:33]
	v_mfma_i32_16x16x64_i8 v[26:29], v[114:117], v[228:231], v[26:29]
	v_mfma_i32_16x16x64_i8 v[10:13], v[114:117], v[236:239], v[10:13]
	v_mfma_i32_16x16x64_i8 v[14:17], v[106:109], v[236:239], v[14:17]
	v_mfma_i32_16x16x64_i8 v[62:65], v[110:113], v[216:219], v[62:65]
	v_mfma_i32_16x16x64_i8 v[58:61], v[118:121], v[216:219], v[58:61]
	v_mfma_i32_16x16x64_i8 v[42:45], v[118:121], v[224:227], v[42:45]
	v_mfma_i32_16x16x64_i8 v[46:49], v[110:113], v[224:227], v[46:49]
	v_mfma_i32_16x16x64_i8 v[30:33], v[110:113], v[232:235], v[30:33]
	v_mfma_i32_16x16x64_i8 v[26:29], v[118:121], v[232:235], v[26:29]
	v_mfma_i32_16x16x64_i8 v[10:13], v[118:121], v[240:243], v[10:13]
	v_mfma_i32_16x16x64_i8 v[14:17], v[110:113], v[240:243], v[14:17]
	s_setprio 0
	s_setprio 1
	v_mfma_i32_16x16x64_i8 v[54:57], v[174:177], v[212:215], v[54:57]
	v_mfma_i32_16x16x64_i8 v[50:53], v[204:207], v[212:215], v[50:53]
	v_mfma_i32_16x16x64_i8 v[34:37], v[204:207], v[220:223], v[34:37]
	v_mfma_i32_16x16x64_i8 v[38:41], v[174:177], v[220:223], v[38:41]
	v_mfma_i32_16x16x64_i8 v[22:25], v[174:177], v[228:231], v[22:25]
	v_mfma_i32_16x16x64_i8 v[18:21], v[204:207], v[228:231], v[18:21]
	v_mfma_i32_16x16x64_i8 v[2:5], v[204:207], v[236:239], v[2:5]
	v_mfma_i32_16x16x64_i8 v[6:9], v[174:177], v[236:239], v[6:9]
	v_mfma_i32_16x16x64_i8 v[54:57], v[200:203], v[216:219], v[54:57]
	v_mfma_i32_16x16x64_i8 v[50:53], v[208:211], v[216:219], v[50:53]
	v_mfma_i32_16x16x64_i8 v[34:37], v[208:211], v[224:227], v[34:37]
	v_mfma_i32_16x16x64_i8 v[38:41], v[200:203], v[224:227], v[38:41]
	v_mfma_i32_16x16x64_i8 v[22:25], v[200:203], v[232:235], v[22:25]
	v_mfma_i32_16x16x64_i8 v[18:21], v[208:211], v[232:235], v[18:21]
	v_mfma_i32_16x16x64_i8 v[2:5], v[208:211], v[240:243], v[2:5]
	v_mfma_i32_16x16x64_i8 v[6:9], v[200:203], v[240:243], v[6:9]
	s_setprio 0
	s_barrier
	s_add_i32 s75, 0, 0x18000
	s_add_i32 s76, 0, 0x1c000
	v_add_u32_e32 v118, s75, v195
	v_add_u32_e32 v164, s76, v195
	ds_read_b128 v[106:109], v118
	ds_read_b128 v[110:113], v118 offset:1024
	ds_read_b128 v[114:117], v118 offset:2048
	ds_read_b128 v[118:121], v118 offset:3072
	ds_read_b128 v[174:177], v164
	ds_read_b128 v[200:203], v164 offset:1024
	ds_read_b128 v[204:207], v164 offset:2048
	ds_read_b128 v[208:211], v164 offset:3072
	s_add_u32 s38, s38, 0x40000
	s_addc_u32 s39, s39, 0
	s_mov_b32 m0, s43
	ds_read_b128 v[212:215], v198 offset:32768
	ds_read_b128 v[216:219], v198 offset:33792
	ds_read_b128 v[220:223], v198 offset:34816
	ds_read_b128 v[224:227], v198 offset:35840
	ds_read_b128 v[228:231], v198 offset:36864
	ds_read_b128 v[232:235], v198 offset:37888
	ds_read_b128 v[236:239], v198 offset:38912
	ds_read_b128 v[240:243], v198 offset:39936
	global_load_lds_dwordx4 v148, s[38:39]
	s_mov_b32 m0, s46
	s_nop 0
	global_load_lds_dwordx4 v150, s[38:39]
	s_waitcnt vmcnt(8)
	s_waitcnt lgkmcnt(0)
	s_barrier
	s_setprio 1
	s_waitcnt lgkmcnt(0)
	v_mfma_i32_16x16x64_i8 v[142:145], v[106:109], v[212:215], v[142:145]
	v_mfma_i32_16x16x64_i8 v[138:141], v[114:117], v[212:215], v[138:141]
	v_mfma_i32_16x16x64_i8 v[122:125], v[114:117], v[220:223], v[122:125]
	v_mfma_i32_16x16x64_i8 v[126:129], v[106:109], v[220:223], v[126:129]
	v_mfma_i32_16x16x64_i8 v[94:97], v[106:109], v[228:231], v[94:97]
	v_mfma_i32_16x16x64_i8 v[90:93], v[114:117], v[228:231], v[90:93]
	v_mfma_i32_16x16x64_i8 v[74:77], v[114:117], v[236:239], v[74:77]
	v_mfma_i32_16x16x64_i8 v[78:81], v[106:109], v[236:239], v[78:81]
	v_mfma_i32_16x16x64_i8 v[142:145], v[110:113], v[216:219], v[142:145]
	v_mfma_i32_16x16x64_i8 v[138:141], v[118:121], v[216:219], v[138:141]
	v_mfma_i32_16x16x64_i8 v[122:125], v[118:121], v[224:227], v[122:125]
	v_mfma_i32_16x16x64_i8 v[126:129], v[110:113], v[224:227], v[126:129]
	v_mfma_i32_16x16x64_i8 v[94:97], v[110:113], v[232:235], v[94:97]
	v_mfma_i32_16x16x64_i8 v[90:93], v[118:121], v[232:235], v[90:93]
	v_mfma_i32_16x16x64_i8 v[74:77], v[118:121], v[240:243], v[74:77]
	v_mfma_i32_16x16x64_i8 v[78:81], v[110:113], v[240:243], v[78:81]
	s_setprio 0
	s_setprio 1
	v_mfma_i32_16x16x64_i8 v[134:137], v[174:177], v[212:215], v[134:137]
	v_mfma_i32_16x16x64_i8 v[130:133], v[204:207], v[212:215], v[130:133]
	v_mfma_i32_16x16x64_i8 v[98:101], v[204:207], v[220:223], v[98:101]
	v_mfma_i32_16x16x64_i8 v[102:105], v[174:177], v[220:223], v[102:105]
	v_mfma_i32_16x16x64_i8 v[86:89], v[174:177], v[228:231], v[86:89]
	v_mfma_i32_16x16x64_i8 v[82:85], v[204:207], v[228:231], v[82:85]
	v_mfma_i32_16x16x64_i8 v[66:69], v[204:207], v[236:239], v[66:69]
	v_mfma_i32_16x16x64_i8 v[70:73], v[174:177], v[236:239], v[70:73]
	v_mfma_i32_16x16x64_i8 v[134:137], v[200:203], v[216:219], v[134:137]
	v_mfma_i32_16x16x64_i8 v[130:133], v[208:211], v[216:219], v[130:133]
	v_mfma_i32_16x16x64_i8 v[98:101], v[208:211], v[224:227], v[98:101]
	v_mfma_i32_16x16x64_i8 v[102:105], v[200:203], v[224:227], v[102:105]
	v_mfma_i32_16x16x64_i8 v[86:89], v[200:203], v[232:235], v[86:89]
	v_mfma_i32_16x16x64_i8 v[82:85], v[208:211], v[232:235], v[82:85]
	v_mfma_i32_16x16x64_i8 v[66:69], v[208:211], v[240:243], v[66:69]
	v_mfma_i32_16x16x64_i8 v[70:73], v[200:203], v[240:243], v[70:73]
	s_setprio 0
	s_barrier
	s_add_u32 s98, s38, 0xfffc0080
	s_addc_u32 s99, s39, -1
	s_add_i32 s38, s75, s41
	s_mov_b32 m0, s38
	ds_read_b128 v[212:215], v198 offset:49152
	ds_read_b128 v[216:219], v198 offset:50176
	ds_read_b128 v[220:223], v198 offset:51200
	ds_read_b128 v[224:227], v198 offset:52224
	ds_read_b128 v[228:231], v198 offset:53248
	ds_read_b128 v[232:235], v198 offset:54272
	ds_read_b128 v[236:239], v198 offset:55296
	ds_read_b128 v[240:243], v198 offset:56320
	s_add_u32 s100, s36, 0x80
	s_addc_u32 s101, s37, 0
	global_load_lds_dwordx4 v148, s[100:101]
	s_add_i32 m0, s38, 0x2000
	s_add_u32 s36, s36, 0x40080
	s_addc_u32 s37, s37, 0
	s_add_i32 s38, s76, s41
	global_load_lds_dwordx4 v150, s[100:101]
	s_mov_b32 m0, s38
	s_nop 0
	global_load_lds_dwordx4 v148, s[36:37]
	s_add_i32 m0, s38, 0x2000
	s_nop 0
	global_load_lds_dwordx4 v150, s[36:37]
	s_mov_b32 m0, s56
	s_nop 0
	global_load_lds_dwordx4 v148, s[98:99]
	s_mov_b32 m0, s57
	s_nop 0
	global_load_lds_dwordx4 v150, s[98:99]
	s_waitcnt vmcnt(8)
	s_waitcnt lgkmcnt(0)
	s_barrier
	s_setprio 1
	s_waitcnt lgkmcnt(0)
	v_mfma_i32_16x16x64_i8 v[62:65], v[106:109], v[212:215], v[62:65]
	v_mfma_i32_16x16x64_i8 v[58:61], v[114:117], v[212:215], v[58:61]
	v_mfma_i32_16x16x64_i8 v[42:45], v[114:117], v[220:223], v[42:45]
	v_mfma_i32_16x16x64_i8 v[46:49], v[106:109], v[220:223], v[46:49]
	v_mfma_i32_16x16x64_i8 v[30:33], v[106:109], v[228:231], v[30:33]
	v_mfma_i32_16x16x64_i8 v[26:29], v[114:117], v[228:231], v[26:29]
	v_mfma_i32_16x16x64_i8 v[10:13], v[114:117], v[236:239], v[10:13]
	v_mfma_i32_16x16x64_i8 v[14:17], v[106:109], v[236:239], v[14:17]
	v_mfma_i32_16x16x64_i8 v[62:65], v[110:113], v[216:219], v[62:65]
	v_mfma_i32_16x16x64_i8 v[58:61], v[118:121], v[216:219], v[58:61]
	v_mfma_i32_16x16x64_i8 v[42:45], v[118:121], v[224:227], v[42:45]
	v_mfma_i32_16x16x64_i8 v[46:49], v[110:113], v[224:227], v[46:49]
	v_mfma_i32_16x16x64_i8 v[30:33], v[110:113], v[232:235], v[30:33]
	v_mfma_i32_16x16x64_i8 v[26:29], v[118:121], v[232:235], v[26:29]
	v_mfma_i32_16x16x64_i8 v[10:13], v[118:121], v[240:243], v[10:13]
	v_mfma_i32_16x16x64_i8 v[14:17], v[110:113], v[240:243], v[14:17]
	s_setprio 0
	s_setprio 1
	v_mfma_i32_16x16x64_i8 v[54:57], v[174:177], v[212:215], v[54:57]
	v_mfma_i32_16x16x64_i8 v[50:53], v[204:207], v[212:215], v[50:53]
	v_mfma_i32_16x16x64_i8 v[34:37], v[204:207], v[220:223], v[34:37]
	v_mfma_i32_16x16x64_i8 v[38:41], v[174:177], v[220:223], v[38:41]
	v_mfma_i32_16x16x64_i8 v[22:25], v[174:177], v[228:231], v[22:25]
	v_mfma_i32_16x16x64_i8 v[18:21], v[204:207], v[228:231], v[18:21]
	v_mfma_i32_16x16x64_i8 v[2:5], v[204:207], v[236:239], v[2:5]
	v_mfma_i32_16x16x64_i8 v[6:9], v[174:177], v[236:239], v[6:9]
	v_mfma_i32_16x16x64_i8 v[54:57], v[200:203], v[216:219], v[54:57]
	v_mfma_i32_16x16x64_i8 v[50:53], v[208:211], v[216:219], v[50:53]
	v_mfma_i32_16x16x64_i8 v[34:37], v[208:211], v[224:227], v[34:37]
	v_mfma_i32_16x16x64_i8 v[38:41], v[200:203], v[224:227], v[38:41]
	v_mfma_i32_16x16x64_i8 v[22:25], v[200:203], v[232:235], v[22:25]
	v_mfma_i32_16x16x64_i8 v[18:21], v[208:211], v[232:235], v[18:21]
	v_mfma_i32_16x16x64_i8 v[2:5], v[208:211], v[240:243], v[2:5]
	v_mfma_i32_16x16x64_i8 v[6:9], v[200:203], v[240:243], v[6:9]
	s_setprio 0
	s_barrier
	s_add_i32 s74, s74, 2
	s_add_u32 s34, s34, 0x100
	s_addc_u32 s35, s35, 0
	s_add_u32 s72, s72, 0x100
	s_addc_u32 s73, s73, 0
	s_cmp_gt_u32 s74, 13
	s_cbranch_scc0 .LBB0_550
	s_and_b64 vcc, exec, s[10:11]
	s_cbranch_vccz .LBB0_553
	s_barrier

.LBB0_574:
	ds_read_b128 v[90:93], v1
	ds_read_b128 v[98:101], v1 offset:1024
	ds_read_b128 v[102:105], v1 offset:2048
	ds_read_b128 v[142:145], v1 offset:3072
	ds_read_b128 v[146:149], v203
	ds_read_b128 v[150:153], v203 offset:1024
	ds_read_b128 v[154:157], v203 offset:2048
	ds_read_b128 v[158:161], v203 offset:3072
	s_add_u32 s24, s22, 0xfffe0080
	s_addc_u32 s25, s23, -1
	s_cmp_eq_u32 s66, 4
	s_cselect_b32 s27, s13, s25
	s_cselect_b32 s26, s46, s24
	s_cselect_b32 s25, s11, s57
	s_cselect_b32 s24, s47, s56
	s_add_i32 m0, s19, 0xc000
	ds_read_b128 v[162:165], v205
	ds_read_b128 v[166:169], v205 offset:1024
	ds_read_b128 v[170:173], v205 offset:2048
	ds_read_b128 v[174:177], v205 offset:3072
	ds_read_b128 v[178:181], v205 offset:4096
	ds_read_b128 v[206:209], v205 offset:5120
	ds_read_b128 v[210:213], v205 offset:6144
	ds_read_b128 v[214:217], v205 offset:7168
	global_load_lds_dwordx4 v190, s[22:23]
	s_add_i32 m0, s19, 0xe000
	s_nop 0
	global_load_lds_dwordx4 v192, s[22:23]
	s_waitcnt vmcnt(8)
	s_waitcnt lgkmcnt(0)
	s_barrier
	s_setprio 1
	s_waitcnt lgkmcnt(0)
	v_mfma_i32_16x16x64_i8 v[94:97], v[90:93], v[162:165], v[94:97]
	v_mfma_i32_16x16x64_i8 v[138:141], v[102:105], v[162:165], v[138:141]
	v_mfma_i32_16x16x64_i8 v[122:125], v[102:105], v[170:173], v[122:125]
	v_mfma_i32_16x16x64_i8 v[126:129], v[90:93], v[170:173], v[126:129]
	v_mfma_i32_16x16x64_i8 v[110:113], v[90:93], v[178:181], v[110:113]
	v_mfma_i32_16x16x64_i8 v[106:109], v[102:105], v[178:181], v[106:109]
	v_mfma_i32_16x16x64_i8 v[74:77], v[102:105], v[210:213], v[74:77]
	v_mfma_i32_16x16x64_i8 v[78:81], v[90:93], v[210:213], v[78:81]
	v_mfma_i32_16x16x64_i8 v[94:97], v[98:101], v[166:169], v[94:97]
	v_mfma_i32_16x16x64_i8 v[138:141], v[142:145], v[166:169], v[138:141]
	v_mfma_i32_16x16x64_i8 v[122:125], v[142:145], v[174:177], v[122:125]
	v_mfma_i32_16x16x64_i8 v[126:129], v[98:101], v[174:177], v[126:129]
	v_mfma_i32_16x16x64_i8 v[110:113], v[98:101], v[206:209], v[110:113]
	v_mfma_i32_16x16x64_i8 v[106:109], v[142:145], v[206:209], v[106:109]
	v_mfma_i32_16x16x64_i8 v[74:77], v[142:145], v[214:217], v[74:77]
	v_mfma_i32_16x16x64_i8 v[78:81], v[98:101], v[214:217], v[78:81]
	s_setprio 0
	s_setprio 1
	v_mfma_i32_16x16x64_i8 v[134:137], v[146:149], v[162:165], v[134:137]
	v_mfma_i32_16x16x64_i8 v[130:133], v[154:157], v[162:165], v[130:133]
	v_mfma_i32_16x16x64_i8 v[114:117], v[154:157], v[170:173], v[114:117]
	v_mfma_i32_16x16x64_i8 v[118:121], v[146:149], v[170:173], v[118:121]
	v_mfma_i32_16x16x64_i8 v[86:89], v[146:149], v[178:181], v[86:89]
	v_mfma_i32_16x16x64_i8 v[82:85], v[154:157], v[178:181], v[82:85]
	v_mfma_i32_16x16x64_i8 v[66:69], v[154:157], v[210:213], v[66:69]
	v_mfma_i32_16x16x64_i8 v[70:73], v[146:149], v[210:213], v[70:73]
	v_mfma_i32_16x16x64_i8 v[134:137], v[150:153], v[166:169], v[134:137]
	v_mfma_i32_16x16x64_i8 v[130:133], v[158:161], v[166:169], v[130:133]
	v_mfma_i32_16x16x64_i8 v[114:117], v[158:161], v[174:177], v[114:117]
	v_mfma_i32_16x16x64_i8 v[118:121], v[150:153], v[174:177], v[118:121]
	v_mfma_i32_16x16x64_i8 v[86:89], v[150:153], v[206:209], v[86:89]
	v_mfma_i32_16x16x64_i8 v[82:85], v[158:161], v[206:209], v[82:85]
	v_mfma_i32_16x16x64_i8 v[66:69], v[158:161], v[214:217], v[66:69]
	v_mfma_i32_16x16x64_i8 v[70:73], v[150:153], v[214:217], v[70:73]
	s_setprio 0
	s_barrier
	s_add_i32 s67, s41, s29
	s_mov_b32 m0, s67
	ds_read_b128 v[162:165], v205 offset:16384
	ds_read_b128 v[166:169], v205 offset:17408
	ds_read_b128 v[170:173], v205 offset:18432
	ds_read_b128 v[174:177], v205 offset:19456
	ds_read_b128 v[178:181], v205 offset:20480
	ds_read_b128 v[206:209], v205 offset:21504
	ds_read_b128 v[210:213], v205 offset:22528
	ds_read_b128 v[214:217], v205 offset:23552
	global_load_lds_dwordx4 v184, s[24:25]
	s_add_i32 m0, s67, 0x2000
	s_add_u32 s68, s24, 0x20000
	s_addc_u32 s69, s25, 0
	s_add_i32 s67, s42, s29
	global_load_lds_dwordx4 v186, s[24:25]
	s_mov_b32 m0, s67
	s_nop 0
	global_load_lds_dwordx4 v184, s[68:69]
	s_add_i32 m0, s67, 0x2000
	s_nop 0
	global_load_lds_dwordx4 v186, s[68:69]
	s_mov_b32 m0, s19
	s_nop 0
	global_load_lds_dwordx4 v184, s[26:27]
	s_mov_b32 m0, s34
	s_nop 0
	global_load_lds_dwordx4 v186, s[26:27]
	s_waitcnt vmcnt(8)
	s_waitcnt lgkmcnt(0)
	s_barrier
	s_setprio 1
	s_waitcnt lgkmcnt(0)
	v_mfma_i32_16x16x64_i8 v[62:65], v[90:93], v[162:165], v[62:65]
	v_mfma_i32_16x16x64_i8 v[58:61], v[102:105], v[162:165], v[58:61]
	v_mfma_i32_16x16x64_i8 v[42:45], v[102:105], v[170:173], v[42:45]
	v_mfma_i32_16x16x64_i8 v[46:49], v[90:93], v[170:173], v[46:49]
	v_mfma_i32_16x16x64_i8 v[30:33], v[90:93], v[178:181], v[30:33]
	v_mfma_i32_16x16x64_i8 v[26:29], v[102:105], v[178:181], v[26:29]
	v_mfma_i32_16x16x64_i8 v[10:13], v[102:105], v[210:213], v[10:13]
	v_mfma_i32_16x16x64_i8 v[14:17], v[90:93], v[210:213], v[14:17]
	v_mfma_i32_16x16x64_i8 v[62:65], v[98:101], v[166:169], v[62:65]
	v_mfma_i32_16x16x64_i8 v[58:61], v[142:145], v[166:169], v[58:61]
	v_mfma_i32_16x16x64_i8 v[42:45], v[142:145], v[174:177], v[42:45]
	v_mfma_i32_16x16x64_i8 v[46:49], v[98:101], v[174:177], v[46:49]
	v_mfma_i32_16x16x64_i8 v[30:33], v[98:101], v[206:209], v[30:33]
	v_mfma_i32_16x16x64_i8 v[26:29], v[142:145], v[206:209], v[26:29]
	v_mfma_i32_16x16x64_i8 v[10:13], v[142:145], v[214:217], v[10:13]
	v_mfma_i32_16x16x64_i8 v[14:17], v[98:101], v[214:217], v[14:17]
	s_setprio 0
	s_setprio 1
	v_mfma_i32_16x16x64_i8 v[54:57], v[146:149], v[162:165], v[54:57]
	v_mfma_i32_16x16x64_i8 v[50:53], v[154:157], v[162:165], v[50:53]
	v_mfma_i32_16x16x64_i8 v[34:37], v[154:157], v[170:173], v[34:37]
	v_mfma_i32_16x16x64_i8 v[38:41], v[146:149], v[170:173], v[38:41]
	v_mfma_i32_16x16x64_i8 v[22:25], v[146:149], v[178:181], v[22:25]
	v_mfma_i32_16x16x64_i8 v[18:21], v[154:157], v[178:181], v[18:21]
	v_mfma_i32_16x16x64_i8 v[2:5], v[154:157], v[210:213], v[2:5]
	v_mfma_i32_16x16x64_i8 v[6:9], v[146:149], v[210:213], v[6:9]
	v_mfma_i32_16x16x64_i8 v[54:57], v[150:153], v[166:169], v[54:57]
	v_mfma_i32_16x16x64_i8 v[50:53], v[158:161], v[166:169], v[50:53]
	v_mfma_i32_16x16x64_i8 v[34:37], v[158:161], v[174:177], v[34:37]
	v_mfma_i32_16x16x64_i8 v[38:41], v[150:153], v[174:177], v[38:41]
	v_mfma_i32_16x16x64_i8 v[22:25], v[150:153], v[206:209], v[22:25]
	v_mfma_i32_16x16x64_i8 v[18:21], v[158:161], v[206:209], v[18:21]
	v_mfma_i32_16x16x64_i8 v[2:5], v[158:161], v[214:217], v[2:5]
	v_mfma_i32_16x16x64_i8 v[6:9], v[150:153], v[214:217], v[6:9]
	s_setprio 0
	s_barrier
	s_add_i32 s67, 0, 0x18000
	s_add_i32 s68, 0, 0x1c000
	v_add_u32_e32 v142, s67, v183
	v_add_u32_e32 v158, s68, v183
	ds_read_b128 v[90:93], v142
	ds_read_b128 v[98:101], v142 offset:1024
	ds_read_b128 v[102:105], v142 offset:2048
	ds_read_b128 v[142:145], v142 offset:3072
	ds_read_b128 v[146:149], v158
	ds_read_b128 v[150:153], v158 offset:1024
	ds_read_b128 v[154:157], v158 offset:2048
	ds_read_b128 v[158:161], v158 offset:3072
	s_add_u32 s26, s26, 0x20000
	s_addc_u32 s27, s27, 0
	s_mov_b32 m0, s35
	ds_read_b128 v[162:165], v205 offset:32768
	ds_read_b128 v[166:169], v205 offset:33792
	ds_read_b128 v[170:173], v205 offset:34816
	ds_read_b128 v[174:177], v205 offset:35840
	ds_read_b128 v[178:181], v205 offset:36864
	ds_read_b128 v[206:209], v205 offset:37888
	ds_read_b128 v[210:213], v205 offset:38912
	ds_read_b128 v[214:217], v205 offset:39936
	global_load_lds_dwordx4 v184, s[26:27]
	s_mov_b32 m0, s36
	s_nop 0
	global_load_lds_dwordx4 v186, s[26:27]
	s_waitcnt vmcnt(8)
	s_waitcnt lgkmcnt(0)
	s_barrier
	s_setprio 1
	s_waitcnt lgkmcnt(0)
	v_mfma_i32_16x16x64_i8 v[94:97], v[90:93], v[162:165], v[94:97]
	v_mfma_i32_16x16x64_i8 v[138:141], v[102:105], v[162:165], v[138:141]
	v_mfma_i32_16x16x64_i8 v[122:125], v[102:105], v[170:173], v[122:125]
	v_mfma_i32_16x16x64_i8 v[126:129], v[90:93], v[170:173], v[126:129]
	v_mfma_i32_16x16x64_i8 v[110:113], v[90:93], v[178:181], v[110:113]
	v_mfma_i32_16x16x64_i8 v[106:109], v[102:105], v[178:181], v[106:109]
	v_mfma_i32_16x16x64_i8 v[74:77], v[102:105], v[210:213], v[74:77]
	v_mfma_i32_16x16x64_i8 v[78:81], v[90:93], v[210:213], v[78:81]
	v_mfma_i32_16x16x64_i8 v[94:97], v[98:101], v[166:169], v[94:97]
	v_mfma_i32_16x16x64_i8 v[138:141], v[142:145], v[166:169], v[138:141]
	v_mfma_i32_16x16x64_i8 v[122:125], v[142:145], v[174:177], v[122:125]
	v_mfma_i32_16x16x64_i8 v[126:129], v[98:101], v[174:177], v[126:129]
	v_mfma_i32_16x16x64_i8 v[110:113], v[98:101], v[206:209], v[110:113]
	v_mfma_i32_16x16x64_i8 v[106:109], v[142:145], v[206:209], v[106:109]
	v_mfma_i32_16x16x64_i8 v[74:77], v[142:145], v[214:217], v[74:77]
	v_mfma_i32_16x16x64_i8 v[78:81], v[98:101], v[214:217], v[78:81]
	s_setprio 0
	s_setprio 1
	v_mfma_i32_16x16x64_i8 v[134:137], v[146:149], v[162:165], v[134:137]
	v_mfma_i32_16x16x64_i8 v[130:133], v[154:157], v[162:165], v[130:133]
	v_mfma_i32_16x16x64_i8 v[114:117], v[154:157], v[170:173], v[114:117]
	v_mfma_i32_16x16x64_i8 v[118:121], v[146:149], v[170:173], v[118:121]
	v_mfma_i32_16x16x64_i8 v[86:89], v[146:149], v[178:181], v[86:89]
	v_mfma_i32_16x16x64_i8 v[82:85], v[154:157], v[178:181], v[82:85]
	v_mfma_i32_16x16x64_i8 v[66:69], v[154:157], v[210:213], v[66:69]
	v_mfma_i32_16x16x64_i8 v[70:73], v[146:149], v[210:213], v[70:73]
	v_mfma_i32_16x16x64_i8 v[134:137], v[150:153], v[166:169], v[134:137]
	v_mfma_i32_16x16x64_i8 v[130:133], v[158:161], v[166:169], v[130:133]
	v_mfma_i32_16x16x64_i8 v[114:117], v[158:161], v[174:177], v[114:117]
	v_mfma_i32_16x16x64_i8 v[118:121], v[150:153], v[174:177], v[118:121]
	v_mfma_i32_16x16x64_i8 v[86:89], v[150:153], v[206:209], v[86:89]
	v_mfma_i32_16x16x64_i8 v[82:85], v[158:161], v[206:209], v[82:85]
	v_mfma_i32_16x16x64_i8 v[66:69], v[158:161], v[214:217], v[66:69]
	v_mfma_i32_16x16x64_i8 v[70:73], v[150:153], v[214:217], v[70:73]
	s_setprio 0
	s_barrier
	s_add_u32 s98, s26, 0xfffe0080
	s_addc_u32 s99, s27, -1
	s_add_i32 s26, s67, s29
	s_mov_b32 m0, s26
	ds_read_b128 v[162:165], v205 offset:49152
	ds_read_b128 v[166:169], v205 offset:50176
	ds_read_b128 v[170:173], v205 offset:51200
	ds_read_b128 v[174:177], v205 offset:52224
	ds_read_b128 v[178:181], v205 offset:53248
	ds_read_b128 v[206:209], v205 offset:54272
	ds_read_b128 v[210:213], v205 offset:55296
	ds_read_b128 v[214:217], v205 offset:56320
	s_add_u32 s100, s24, 0x80
	s_addc_u32 s101, s25, 0
	global_load_lds_dwordx4 v184, s[100:101]
	s_add_i32 m0, s26, 0x2000
	s_add_u32 s24, s24, 0x20080
	s_addc_u32 s25, s25, 0
	s_add_i32 s26, s68, s29
	global_load_lds_dwordx4 v186, s[100:101]
	s_mov_b32 m0, s26
	s_nop 0
	global_load_lds_dwordx4 v184, s[24:25]
	s_add_i32 m0, s26, 0x2000
	s_nop 0
	global_load_lds_dwordx4 v186, s[24:25]
	s_mov_b32 m0, s38
	s_nop 0
	global_load_lds_dwordx4 v184, s[98:99]
	s_mov_b32 m0, s39
	s_nop 0
	global_load_lds_dwordx4 v186, s[98:99]
	s_waitcnt vmcnt(8)
	s_waitcnt lgkmcnt(0)
	s_barrier
	s_setprio 1
	s_waitcnt lgkmcnt(0)
	v_mfma_i32_16x16x64_i8 v[62:65], v[90:93], v[162:165], v[62:65]
	v_mfma_i32_16x16x64_i8 v[58:61], v[102:105], v[162:165], v[58:61]
	v_mfma_i32_16x16x64_i8 v[42:45], v[102:105], v[170:173], v[42:45]
	v_mfma_i32_16x16x64_i8 v[46:49], v[90:93], v[170:173], v[46:49]
	v_mfma_i32_16x16x64_i8 v[30:33], v[90:93], v[178:181], v[30:33]
	v_mfma_i32_16x16x64_i8 v[26:29], v[102:105], v[178:181], v[26:29]
	v_mfma_i32_16x16x64_i8 v[10:13], v[102:105], v[210:213], v[10:13]
	v_mfma_i32_16x16x64_i8 v[14:17], v[90:93], v[210:213], v[14:17]
	v_mfma_i32_16x16x64_i8 v[62:65], v[98:101], v[166:169], v[62:65]
	v_mfma_i32_16x16x64_i8 v[58:61], v[142:145], v[166:169], v[58:61]
	v_mfma_i32_16x16x64_i8 v[42:45], v[142:145], v[174:177], v[42:45]
	v_mfma_i32_16x16x64_i8 v[46:49], v[98:101], v[174:177], v[46:49]
	v_mfma_i32_16x16x64_i8 v[30:33], v[98:101], v[206:209], v[30:33]
	v_mfma_i32_16x16x64_i8 v[26:29], v[142:145], v[206:209], v[26:29]
	v_mfma_i32_16x16x64_i8 v[10:13], v[142:145], v[214:217], v[10:13]
	v_mfma_i32_16x16x64_i8 v[14:17], v[98:101], v[214:217], v[14:17]
	s_setprio 0
	s_setprio 1
	v_mfma_i32_16x16x64_i8 v[54:57], v[146:149], v[162:165], v[54:57]
	v_mfma_i32_16x16x64_i8 v[50:53], v[154:157], v[162:165], v[50:53]
	v_mfma_i32_16x16x64_i8 v[34:37], v[154:157], v[170:173], v[34:37]
	v_mfma_i32_16x16x64_i8 v[38:41], v[146:149], v[170:173], v[38:41]
	v_mfma_i32_16x16x64_i8 v[22:25], v[146:149], v[178:181], v[22:25]
	v_mfma_i32_16x16x64_i8 v[18:21], v[154:157], v[178:181], v[18:21]
	v_mfma_i32_16x16x64_i8 v[2:5], v[154:157], v[210:213], v[2:5]
	v_mfma_i32_16x16x64_i8 v[6:9], v[146:149], v[210:213], v[6:9]
	v_mfma_i32_16x16x64_i8 v[54:57], v[150:153], v[166:169], v[54:57]
	v_mfma_i32_16x16x64_i8 v[50:53], v[158:161], v[166:169], v[50:53]
	v_mfma_i32_16x16x64_i8 v[34:37], v[158:161], v[174:177], v[34:37]
	v_mfma_i32_16x16x64_i8 v[38:41], v[150:153], v[174:177], v[38:41]
	v_mfma_i32_16x16x64_i8 v[22:25], v[150:153], v[206:209], v[22:25]
	v_mfma_i32_16x16x64_i8 v[18:21], v[158:161], v[206:209], v[18:21]
	v_mfma_i32_16x16x64_i8 v[2:5], v[158:161], v[214:217], v[2:5]
	v_mfma_i32_16x16x64_i8 v[6:9], v[150:153], v[214:217], v[6:9]
	s_setprio 0
	s_barrier
	s_add_i32 s66, s66, 2
	s_add_u32 s22, s22, 0x100
	s_addc_u32 s23, s23, 0
	s_add_u32 s56, s56, 0x100
	s_addc_u32 s57, s57, 0
	s_cmp_gt_u32 s66, 5
	s_cbranch_scc0 .LBB0_574
	s_and_b64 vcc, exec, s[8:9]
	s_cbranch_vccz .LBB0_577
	s_barrier

.LBB0_709:
	ds_read_b128 v[130:133], v178
	ds_read_b128 v[134:137], v178 offset:1024
	ds_read_b128 v[138:141], v178 offset:2048
	ds_read_b128 v[142:145], v178 offset:3072
	ds_read_b128 v[146:149], v179
	ds_read_b128 v[150:153], v179 offset:1024
	ds_read_b128 v[154:157], v179 offset:2048
	ds_read_b128 v[158:161], v179 offset:3072
	s_add_u32 s38, s36, 0xfff80080
	s_addc_u32 s39, s37, -1
	s_cmp_eq_u32 s78, 28
	s_cselect_b32 s41, s27, s39
	s_cselect_b32 s40, s74, s38
	s_cselect_b32 s39, s25, s77
	s_cselect_b32 s38, s75, s76
	s_add_i32 m0, s35, 0xc000
	ds_read_b128 v[184:187], v180
	ds_read_b128 v[188:191], v180 offset:1024
	ds_read_b128 v[192:195], v180 offset:2048
	ds_read_b128 v[196:199], v180 offset:3072
	ds_read_b128 v[200:203], v180 offset:4096
	ds_read_b128 v[204:207], v180 offset:5120
	ds_read_b128 v[208:211], v180 offset:6144
	ds_read_b128 v[212:215], v180 offset:7168
	global_load_lds_dwordx4 v168, s[36:37]
	s_add_i32 m0, s35, 0xe000
	s_nop 0
	global_load_lds_dwordx4 v170, s[36:37]
	s_waitcnt vmcnt(8)
	s_waitcnt lgkmcnt(0)
	s_barrier
	s_setprio 1
	s_waitcnt lgkmcnt(0)
	v_mfma_i32_16x16x64_i8 v[126:129], v[130:133], v[184:187], v[126:129]
	v_mfma_i32_16x16x64_i8 v[122:125], v[138:141], v[184:187], v[122:125]
	v_mfma_i32_16x16x64_i8 v[106:109], v[138:141], v[192:195], v[106:109]
	v_mfma_i32_16x16x64_i8 v[110:113], v[130:133], v[192:195], v[110:113]
	v_mfma_i32_16x16x64_i8 v[94:97], v[130:133], v[200:203], v[94:97]
	v_mfma_i32_16x16x64_i8 v[90:93], v[138:141], v[200:203], v[90:93]
	v_mfma_i32_16x16x64_i8 v[74:77], v[138:141], v[208:211], v[74:77]
	v_mfma_i32_16x16x64_i8 v[78:81], v[130:133], v[208:211], v[78:81]
	v_mfma_i32_16x16x64_i8 v[126:129], v[134:137], v[188:191], v[126:129]
	v_mfma_i32_16x16x64_i8 v[122:125], v[142:145], v[188:191], v[122:125]
	v_mfma_i32_16x16x64_i8 v[106:109], v[142:145], v[196:199], v[106:109]
	v_mfma_i32_16x16x64_i8 v[110:113], v[134:137], v[196:199], v[110:113]
	v_mfma_i32_16x16x64_i8 v[94:97], v[134:137], v[204:207], v[94:97]
	v_mfma_i32_16x16x64_i8 v[90:93], v[142:145], v[204:207], v[90:93]
	v_mfma_i32_16x16x64_i8 v[74:77], v[142:145], v[212:215], v[74:77]
	v_mfma_i32_16x16x64_i8 v[78:81], v[134:137], v[212:215], v[78:81]
	s_setprio 0
	s_setprio 1
	v_mfma_i32_16x16x64_i8 v[118:121], v[146:149], v[184:187], v[118:121]
	v_mfma_i32_16x16x64_i8 v[114:117], v[154:157], v[184:187], v[114:117]
	v_mfma_i32_16x16x64_i8 v[98:101], v[154:157], v[192:195], v[98:101]
	v_mfma_i32_16x16x64_i8 v[102:105], v[146:149], v[192:195], v[102:105]
	v_mfma_i32_16x16x64_i8 v[86:89], v[146:149], v[200:203], v[86:89]
	v_mfma_i32_16x16x64_i8 v[82:85], v[154:157], v[200:203], v[82:85]
	v_mfma_i32_16x16x64_i8 v[66:69], v[154:157], v[208:211], v[66:69]
	v_mfma_i32_16x16x64_i8 v[70:73], v[146:149], v[208:211], v[70:73]
	v_mfma_i32_16x16x64_i8 v[118:121], v[150:153], v[188:191], v[118:121]
	v_mfma_i32_16x16x64_i8 v[114:117], v[158:161], v[188:191], v[114:117]
	v_mfma_i32_16x16x64_i8 v[98:101], v[158:161], v[196:199], v[98:101]
	v_mfma_i32_16x16x64_i8 v[102:105], v[150:153], v[196:199], v[102:105]
	v_mfma_i32_16x16x64_i8 v[86:89], v[150:153], v[204:207], v[86:89]
	v_mfma_i32_16x16x64_i8 v[82:85], v[158:161], v[204:207], v[82:85]
	v_mfma_i32_16x16x64_i8 v[66:69], v[158:161], v[212:215], v[66:69]
	v_mfma_i32_16x16x64_i8 v[70:73], v[150:153], v[212:215], v[70:73]
	s_setprio 0
	s_barrier
	s_add_i32 s79, s0, s42
	s_mov_b32 m0, s79
	ds_read_b128 v[184:187], v180 offset:16384
	ds_read_b128 v[188:191], v180 offset:17408
	ds_read_b128 v[192:195], v180 offset:18432
	ds_read_b128 v[196:199], v180 offset:19456
	ds_read_b128 v[200:203], v180 offset:20480
	ds_read_b128 v[204:207], v180 offset:21504
	ds_read_b128 v[208:211], v180 offset:22528
	ds_read_b128 v[212:215], v180 offset:23552
	global_load_lds_dwordx4 v162, s[38:39]
	s_add_i32 m0, s79, 0x2000
	s_add_u32 s82, s38, 0x80000
	s_addc_u32 s83, s39, 0
	s_add_i32 s79, s68, s42
	global_load_lds_dwordx4 v164, s[38:39]
	s_mov_b32 m0, s79
	s_nop 0
	global_load_lds_dwordx4 v162, s[82:83]
	s_add_i32 m0, s79, 0x2000
	s_nop 0
	global_load_lds_dwordx4 v164, s[82:83]
	s_mov_b32 m0, s35
	s_nop 0
	global_load_lds_dwordx4 v162, s[40:41]
	s_mov_b32 m0, s46
	s_nop 0
	global_load_lds_dwordx4 v164, s[40:41]
	s_waitcnt vmcnt(8)
	s_waitcnt lgkmcnt(0)
	s_barrier
	s_setprio 1
	s_waitcnt lgkmcnt(0)
	v_mfma_i32_16x16x64_i8 v[62:65], v[130:133], v[184:187], v[62:65]
	v_mfma_i32_16x16x64_i8 v[58:61], v[138:141], v[184:187], v[58:61]
	v_mfma_i32_16x16x64_i8 v[42:45], v[138:141], v[192:195], v[42:45]
	v_mfma_i32_16x16x64_i8 v[50:53], v[130:133], v[192:195], v[50:53]
	v_mfma_i32_16x16x64_i8 v[34:37], v[130:133], v[200:203], v[34:37]
	v_mfma_i32_16x16x64_i8 v[26:29], v[138:141], v[200:203], v[26:29]
	v_mfma_i32_16x16x64_i8 v[10:13], v[138:141], v[208:211], v[10:13]
	v_mfma_i32_16x16x64_i8 v[18:21], v[130:133], v[208:211], v[18:21]
	v_mfma_i32_16x16x64_i8 v[62:65], v[134:137], v[188:191], v[62:65]
	v_mfma_i32_16x16x64_i8 v[58:61], v[142:145], v[188:191], v[58:61]
	v_mfma_i32_16x16x64_i8 v[42:45], v[142:145], v[196:199], v[42:45]
	v_mfma_i32_16x16x64_i8 v[50:53], v[134:137], v[196:199], v[50:53]
	v_mfma_i32_16x16x64_i8 v[34:37], v[134:137], v[204:207], v[34:37]
	v_mfma_i32_16x16x64_i8 v[26:29], v[142:145], v[204:207], v[26:29]
	v_mfma_i32_16x16x64_i8 v[10:13], v[142:145], v[212:215], v[10:13]
	v_mfma_i32_16x16x64_i8 v[18:21], v[134:137], v[212:215], v[18:21]
	s_setprio 0
	s_setprio 1
	v_mfma_i32_16x16x64_i8 v[54:57], v[146:149], v[184:187], v[54:57]
	v_mfma_i32_16x16x64_i8 v[46:49], v[154:157], v[184:187], v[46:49]
	v_mfma_i32_16x16x64_i8 v[30:33], v[154:157], v[192:195], v[30:33]
	v_mfma_i32_16x16x64_i8 v[38:41], v[146:149], v[192:195], v[38:41]
	v_mfma_i32_16x16x64_i8 v[22:25], v[146:149], v[200:203], v[22:25]
	v_mfma_i32_16x16x64_i8 v[14:17], v[154:157], v[200:203], v[14:17]
	v_mfma_i32_16x16x64_i8 v[2:5], v[154:157], v[208:211], v[2:5]
	v_mfma_i32_16x16x64_i8 v[6:9], v[146:149], v[208:211], v[6:9]
	v_mfma_i32_16x16x64_i8 v[54:57], v[150:153], v[188:191], v[54:57]
	v_mfma_i32_16x16x64_i8 v[46:49], v[158:161], v[188:191], v[46:49]
	v_mfma_i32_16x16x64_i8 v[30:33], v[158:161], v[196:199], v[30:33]
	v_mfma_i32_16x16x64_i8 v[38:41], v[150:153], v[196:199], v[38:41]
	v_mfma_i32_16x16x64_i8 v[22:25], v[150:153], v[204:207], v[22:25]
	v_mfma_i32_16x16x64_i8 v[14:17], v[158:161], v[204:207], v[14:17]
	v_mfma_i32_16x16x64_i8 v[2:5], v[158:161], v[212:215], v[2:5]
	v_mfma_i32_16x16x64_i8 v[6:9], v[150:153], v[212:215], v[6:9]
	s_setprio 0
	s_barrier
	s_add_i32 s79, 0, 0x18000
	s_add_i32 s80, 0, 0x1c000
	v_add_u32_e32 v142, s79, v176
	v_add_u32_e32 v158, s80, v176
	ds_read_b128 v[130:133], v142
	ds_read_b128 v[134:137], v142 offset:1024
	ds_read_b128 v[138:141], v142 offset:2048
	ds_read_b128 v[142:145], v142 offset:3072
	ds_read_b128 v[146:149], v158
	ds_read_b128 v[150:153], v158 offset:1024
	ds_read_b128 v[154:157], v158 offset:2048
	ds_read_b128 v[158:161], v158 offset:3072
	s_add_u32 s40, s40, 0x80000
	s_addc_u32 s41, s41, 0
	s_mov_b32 m0, s47
	ds_read_b128 v[184:187], v180 offset:32768
	ds_read_b128 v[188:191], v180 offset:33792
	ds_read_b128 v[192:195], v180 offset:34816
	ds_read_b128 v[196:199], v180 offset:35840
	ds_read_b128 v[200:203], v180 offset:36864
	ds_read_b128 v[204:207], v180 offset:37888
	ds_read_b128 v[208:211], v180 offset:38912
	ds_read_b128 v[212:215], v180 offset:39936
	global_load_lds_dwordx4 v162, s[40:41]
	s_mov_b32 m0, s54
	s_nop 0
	global_load_lds_dwordx4 v164, s[40:41]
	s_waitcnt vmcnt(8)
	s_waitcnt lgkmcnt(0)
	s_barrier
	s_setprio 1
	s_waitcnt lgkmcnt(0)
	v_mfma_i32_16x16x64_i8 v[126:129], v[130:133], v[184:187], v[126:129]
	v_mfma_i32_16x16x64_i8 v[122:125], v[138:141], v[184:187], v[122:125]
	v_mfma_i32_16x16x64_i8 v[106:109], v[138:141], v[192:195], v[106:109]
	v_mfma_i32_16x16x64_i8 v[110:113], v[130:133], v[192:195], v[110:113]
	v_mfma_i32_16x16x64_i8 v[94:97], v[130:133], v[200:203], v[94:97]
	v_mfma_i32_16x16x64_i8 v[90:93], v[138:141], v[200:203], v[90:93]
	v_mfma_i32_16x16x64_i8 v[74:77], v[138:141], v[208:211], v[74:77]
	v_mfma_i32_16x16x64_i8 v[78:81], v[130:133], v[208:211], v[78:81]
	v_mfma_i32_16x16x64_i8 v[126:129], v[134:137], v[188:191], v[126:129]
	v_mfma_i32_16x16x64_i8 v[122:125], v[142:145], v[188:191], v[122:125]
	v_mfma_i32_16x16x64_i8 v[106:109], v[142:145], v[196:199], v[106:109]
	v_mfma_i32_16x16x64_i8 v[110:113], v[134:137], v[196:199], v[110:113]
	v_mfma_i32_16x16x64_i8 v[94:97], v[134:137], v[204:207], v[94:97]
	v_mfma_i32_16x16x64_i8 v[90:93], v[142:145], v[204:207], v[90:93]
	v_mfma_i32_16x16x64_i8 v[74:77], v[142:145], v[212:215], v[74:77]
	v_mfma_i32_16x16x64_i8 v[78:81], v[134:137], v[212:215], v[78:81]
	s_setprio 0
	s_setprio 1
	v_mfma_i32_16x16x64_i8 v[118:121], v[146:149], v[184:187], v[118:121]
	v_mfma_i32_16x16x64_i8 v[114:117], v[154:157], v[184:187], v[114:117]
	v_mfma_i32_16x16x64_i8 v[98:101], v[154:157], v[192:195], v[98:101]
	v_mfma_i32_16x16x64_i8 v[102:105], v[146:149], v[192:195], v[102:105]
	v_mfma_i32_16x16x64_i8 v[86:89], v[146:149], v[200:203], v[86:89]
	v_mfma_i32_16x16x64_i8 v[82:85], v[154:157], v[200:203], v[82:85]
	v_mfma_i32_16x16x64_i8 v[66:69], v[154:157], v[208:211], v[66:69]
	v_mfma_i32_16x16x64_i8 v[70:73], v[146:149], v[208:211], v[70:73]
	v_mfma_i32_16x16x64_i8 v[118:121], v[150:153], v[188:191], v[118:121]
	v_mfma_i32_16x16x64_i8 v[114:117], v[158:161], v[188:191], v[114:117]
	v_mfma_i32_16x16x64_i8 v[98:101], v[158:161], v[196:199], v[98:101]
	v_mfma_i32_16x16x64_i8 v[102:105], v[150:153], v[196:199], v[102:105]
	v_mfma_i32_16x16x64_i8 v[86:89], v[150:153], v[204:207], v[86:89]
	v_mfma_i32_16x16x64_i8 v[82:85], v[158:161], v[204:207], v[82:85]
	v_mfma_i32_16x16x64_i8 v[66:69], v[158:161], v[212:215], v[66:69]
	v_mfma_i32_16x16x64_i8 v[70:73], v[150:153], v[212:215], v[70:73]
	s_setprio 0
	s_barrier
	s_add_u32 s98, s40, 0xfff80080
	s_addc_u32 s99, s41, -1
	s_add_i32 s40, s79, s42
	s_mov_b32 m0, s40
	ds_read_b128 v[184:187], v180 offset:49152
	ds_read_b128 v[188:191], v180 offset:50176
	ds_read_b128 v[192:195], v180 offset:51200
	ds_read_b128 v[196:199], v180 offset:52224
	ds_read_b128 v[200:203], v180 offset:53248
	ds_read_b128 v[204:207], v180 offset:54272
	ds_read_b128 v[208:211], v180 offset:55296
	ds_read_b128 v[212:215], v180 offset:56320
	s_add_u32 s100, s38, 0x80
	s_addc_u32 s101, s39, 0
	global_load_lds_dwordx4 v162, s[100:101]
	s_add_i32 m0, s40, 0x2000
	s_add_u32 s38, s38, 0x80080
	s_addc_u32 s39, s39, 0
	s_add_i32 s40, s80, s42
	global_load_lds_dwordx4 v164, s[100:101]
	s_mov_b32 m0, s40
	s_nop 0
	global_load_lds_dwordx4 v162, s[38:39]
	s_add_i32 m0, s40, 0x2000
	s_nop 0
	global_load_lds_dwordx4 v164, s[38:39]
	s_mov_b32 m0, s66
	s_nop 0
	global_load_lds_dwordx4 v162, s[98:99]
	s_mov_b32 m0, s67
	s_nop 0
	global_load_lds_dwordx4 v164, s[98:99]
	s_waitcnt vmcnt(8)
	s_waitcnt lgkmcnt(0)
	s_barrier
	s_setprio 1
	s_waitcnt lgkmcnt(0)
	v_mfma_i32_16x16x64_i8 v[62:65], v[130:133], v[184:187], v[62:65]
	v_mfma_i32_16x16x64_i8 v[58:61], v[138:141], v[184:187], v[58:61]
	v_mfma_i32_16x16x64_i8 v[42:45], v[138:141], v[192:195], v[42:45]
	v_mfma_i32_16x16x64_i8 v[50:53], v[130:133], v[192:195], v[50:53]
	v_mfma_i32_16x16x64_i8 v[34:37], v[130:133], v[200:203], v[34:37]
	v_mfma_i32_16x16x64_i8 v[26:29], v[138:141], v[200:203], v[26:29]
	v_mfma_i32_16x16x64_i8 v[10:13], v[138:141], v[208:211], v[10:13]
	v_mfma_i32_16x16x64_i8 v[18:21], v[130:133], v[208:211], v[18:21]
	v_mfma_i32_16x16x64_i8 v[62:65], v[134:137], v[188:191], v[62:65]
	v_mfma_i32_16x16x64_i8 v[58:61], v[142:145], v[188:191], v[58:61]
	v_mfma_i32_16x16x64_i8 v[42:45], v[142:145], v[196:199], v[42:45]
	v_mfma_i32_16x16x64_i8 v[50:53], v[134:137], v[196:199], v[50:53]
	v_mfma_i32_16x16x64_i8 v[34:37], v[134:137], v[204:207], v[34:37]
	v_mfma_i32_16x16x64_i8 v[26:29], v[142:145], v[204:207], v[26:29]
	v_mfma_i32_16x16x64_i8 v[10:13], v[142:145], v[212:215], v[10:13]
	v_mfma_i32_16x16x64_i8 v[18:21], v[134:137], v[212:215], v[18:21]
	s_setprio 0
	s_setprio 1
	v_mfma_i32_16x16x64_i8 v[54:57], v[146:149], v[184:187], v[54:57]
	v_mfma_i32_16x16x64_i8 v[46:49], v[154:157], v[184:187], v[46:49]
	v_mfma_i32_16x16x64_i8 v[30:33], v[154:157], v[192:195], v[30:33]
	v_mfma_i32_16x16x64_i8 v[38:41], v[146:149], v[192:195], v[38:41]
	v_mfma_i32_16x16x64_i8 v[22:25], v[146:149], v[200:203], v[22:25]
	v_mfma_i32_16x16x64_i8 v[14:17], v[154:157], v[200:203], v[14:17]
	v_mfma_i32_16x16x64_i8 v[2:5], v[154:157], v[208:211], v[2:5]
	v_mfma_i32_16x16x64_i8 v[6:9], v[146:149], v[208:211], v[6:9]
	v_mfma_i32_16x16x64_i8 v[54:57], v[150:153], v[188:191], v[54:57]
	v_mfma_i32_16x16x64_i8 v[46:49], v[158:161], v[188:191], v[46:49]
	v_mfma_i32_16x16x64_i8 v[30:33], v[158:161], v[196:199], v[30:33]
	v_mfma_i32_16x16x64_i8 v[38:41], v[150:153], v[196:199], v[38:41]
	v_mfma_i32_16x16x64_i8 v[22:25], v[150:153], v[204:207], v[22:25]
	v_mfma_i32_16x16x64_i8 v[14:17], v[158:161], v[204:207], v[14:17]
	v_mfma_i32_16x16x64_i8 v[2:5], v[158:161], v[212:215], v[2:5]
	v_mfma_i32_16x16x64_i8 v[6:9], v[150:153], v[212:215], v[6:9]
	s_setprio 0
	s_barrier
	s_add_i32 s78, s78, 2
	s_add_u32 s36, s36, 0x100
	s_addc_u32 s37, s37, 0
	s_add_u32 s76, s76, 0x100
	s_addc_u32 s77, s77, 0
	s_cmp_gt_u32 s78, 29
	s_cbranch_scc0 .LBB0_709
	s_and_b64 vcc, exec, s[12:13]
	s_cbranch_vccz .LBB0_712
	s_barrier

.LBB0_848:
	ds_read_b128 v[106:109], v173
	ds_read_b128 v[110:113], v173 offset:1024
	ds_read_b128 v[122:125], v173 offset:2048
	ds_read_b128 v[126:129], v173 offset:3072
	ds_read_b128 v[176:179], v174
	ds_read_b128 v[184:187], v174 offset:1024
	ds_read_b128 v[188:191], v174 offset:2048
	ds_read_b128 v[192:195], v174 offset:3072
	s_add_u32 s34, s30, 0xfff80080
	s_addc_u32 s35, s31, -1
	s_cmp_eq_u32 s70, 28
	s_cselect_b32 s37, s23, s35
	s_cselect_b32 s36, s66, s34
	s_cselect_b32 s35, s19, s69
	s_cselect_b32 s34, s67, s68
	s_add_i32 m0, s29, 0xc000
	ds_read_b128 v[196:199], v175
	ds_read_b128 v[200:203], v175 offset:1024
	ds_read_b128 v[204:207], v175 offset:2048
	ds_read_b128 v[208:211], v175 offset:3072
	ds_read_b128 v[212:215], v175 offset:4096
	ds_read_b128 v[216:219], v175 offset:5120
	ds_read_b128 v[220:223], v175 offset:6144
	ds_read_b128 v[224:227], v175 offset:7168
	global_load_lds_dwordx4 v152, s[30:31]
	s_add_i32 m0, s29, 0xe000
	s_nop 0
	global_load_lds_dwordx4 v154, s[30:31]
	s_waitcnt vmcnt(8)
	s_waitcnt lgkmcnt(0)
	s_barrier
	s_setprio 1
	s_waitcnt lgkmcnt(0)
	v_mfma_i32_16x16x64_i8 v[142:145], v[106:109], v[196:199], v[142:145]
	v_mfma_i32_16x16x64_i8 v[138:141], v[122:125], v[196:199], v[138:141]
	v_mfma_i32_16x16x64_i8 v[114:117], v[122:125], v[204:207], v[114:117]
	v_mfma_i32_16x16x64_i8 v[118:121], v[106:109], v[204:207], v[118:121]
	v_mfma_i32_16x16x64_i8 v[94:97], v[106:109], v[212:215], v[94:97]
	v_mfma_i32_16x16x64_i8 v[90:93], v[122:125], v[212:215], v[90:93]
	v_mfma_i32_16x16x64_i8 v[74:77], v[122:125], v[220:223], v[74:77]
	v_mfma_i32_16x16x64_i8 v[78:81], v[106:109], v[220:223], v[78:81]
	v_mfma_i32_16x16x64_i8 v[142:145], v[110:113], v[200:203], v[142:145]
	v_mfma_i32_16x16x64_i8 v[138:141], v[126:129], v[200:203], v[138:141]
	v_mfma_i32_16x16x64_i8 v[114:117], v[126:129], v[208:211], v[114:117]
	v_mfma_i32_16x16x64_i8 v[118:121], v[110:113], v[208:211], v[118:121]
	v_mfma_i32_16x16x64_i8 v[94:97], v[110:113], v[216:219], v[94:97]
	v_mfma_i32_16x16x64_i8 v[90:93], v[126:129], v[216:219], v[90:93]
	v_mfma_i32_16x16x64_i8 v[74:77], v[126:129], v[224:227], v[74:77]
	v_mfma_i32_16x16x64_i8 v[78:81], v[110:113], v[224:227], v[78:81]
	s_setprio 0
	s_setprio 1
	v_mfma_i32_16x16x64_i8 v[134:137], v[176:179], v[196:199], v[134:137]
	v_mfma_i32_16x16x64_i8 v[130:133], v[188:191], v[196:199], v[130:133]
	v_mfma_i32_16x16x64_i8 v[98:101], v[188:191], v[204:207], v[98:101]
	v_mfma_i32_16x16x64_i8 v[102:105], v[176:179], v[204:207], v[102:105]
	v_mfma_i32_16x16x64_i8 v[86:89], v[176:179], v[212:215], v[86:89]
	v_mfma_i32_16x16x64_i8 v[82:85], v[188:191], v[212:215], v[82:85]
	v_mfma_i32_16x16x64_i8 v[66:69], v[188:191], v[220:223], v[66:69]
	v_mfma_i32_16x16x64_i8 v[70:73], v[176:179], v[220:223], v[70:73]
	v_mfma_i32_16x16x64_i8 v[134:137], v[184:187], v[200:203], v[134:137]
	v_mfma_i32_16x16x64_i8 v[130:133], v[192:195], v[200:203], v[130:133]
	v_mfma_i32_16x16x64_i8 v[98:101], v[192:195], v[208:211], v[98:101]
	v_mfma_i32_16x16x64_i8 v[102:105], v[184:187], v[208:211], v[102:105]
	v_mfma_i32_16x16x64_i8 v[86:89], v[184:187], v[216:219], v[86:89]
	v_mfma_i32_16x16x64_i8 v[82:85], v[192:195], v[216:219], v[82:85]
	v_mfma_i32_16x16x64_i8 v[66:69], v[192:195], v[224:227], v[66:69]
	v_mfma_i32_16x16x64_i8 v[70:73], v[184:187], v[224:227], v[70:73]
	s_setprio 0
	s_barrier
	s_add_i32 s71, s51, s39
	s_mov_b32 m0, s71
	ds_read_b128 v[196:199], v175 offset:16384
	ds_read_b128 v[200:203], v175 offset:17408
	ds_read_b128 v[204:207], v175 offset:18432
	ds_read_b128 v[208:211], v175 offset:19456
	ds_read_b128 v[212:215], v175 offset:20480
	ds_read_b128 v[216:219], v175 offset:21504
	ds_read_b128 v[220:223], v175 offset:22528
	ds_read_b128 v[224:227], v175 offset:23552
	global_load_lds_dwordx4 v146, s[34:35]
	s_add_i32 m0, s71, 0x2000
	s_add_u32 s72, s34, 0x80000
	s_addc_u32 s73, s35, 0
	s_add_i32 s71, s52, s39
	global_load_lds_dwordx4 v148, s[34:35]
	s_mov_b32 m0, s71
	s_nop 0
	global_load_lds_dwordx4 v146, s[72:73]
	s_add_i32 m0, s71, 0x2000
	s_nop 0
	global_load_lds_dwordx4 v148, s[72:73]
	s_mov_b32 m0, s29
	s_nop 0
	global_load_lds_dwordx4 v146, s[36:37]
	s_mov_b32 m0, s40
	s_nop 0
	global_load_lds_dwordx4 v148, s[36:37]
	s_waitcnt vmcnt(8)
	s_waitcnt lgkmcnt(0)
	s_barrier
	s_setprio 1
	s_waitcnt lgkmcnt(0)
	v_mfma_i32_16x16x64_i8 v[62:65], v[106:109], v[196:199], v[62:65]
	v_mfma_i32_16x16x64_i8 v[58:61], v[122:125], v[196:199], v[58:61]
	v_mfma_i32_16x16x64_i8 v[42:45], v[122:125], v[204:207], v[42:45]
	v_mfma_i32_16x16x64_i8 v[46:49], v[106:109], v[204:207], v[46:49]
	v_mfma_i32_16x16x64_i8 v[30:33], v[106:109], v[212:215], v[30:33]
	v_mfma_i32_16x16x64_i8 v[26:29], v[122:125], v[212:215], v[26:29]
	v_mfma_i32_16x16x64_i8 v[10:13], v[122:125], v[220:223], v[10:13]
	v_mfma_i32_16x16x64_i8 v[14:17], v[106:109], v[220:223], v[14:17]
	v_mfma_i32_16x16x64_i8 v[62:65], v[110:113], v[200:203], v[62:65]
	v_mfma_i32_16x16x64_i8 v[58:61], v[126:129], v[200:203], v[58:61]
	v_mfma_i32_16x16x64_i8 v[42:45], v[126:129], v[208:211], v[42:45]
	v_mfma_i32_16x16x64_i8 v[46:49], v[110:113], v[208:211], v[46:49]
	v_mfma_i32_16x16x64_i8 v[30:33], v[110:113], v[216:219], v[30:33]
	v_mfma_i32_16x16x64_i8 v[26:29], v[126:129], v[216:219], v[26:29]
	v_mfma_i32_16x16x64_i8 v[10:13], v[126:129], v[224:227], v[10:13]
	v_mfma_i32_16x16x64_i8 v[14:17], v[110:113], v[224:227], v[14:17]
	s_setprio 0
	s_setprio 1
	v_mfma_i32_16x16x64_i8 v[54:57], v[176:179], v[196:199], v[54:57]
	v_mfma_i32_16x16x64_i8 v[50:53], v[188:191], v[196:199], v[50:53]
	v_mfma_i32_16x16x64_i8 v[34:37], v[188:191], v[204:207], v[34:37]
	v_mfma_i32_16x16x64_i8 v[38:41], v[176:179], v[204:207], v[38:41]
	v_mfma_i32_16x16x64_i8 v[22:25], v[176:179], v[212:215], v[22:25]
	v_mfma_i32_16x16x64_i8 v[18:21], v[188:191], v[212:215], v[18:21]
	v_mfma_i32_16x16x64_i8 v[2:5], v[188:191], v[220:223], v[2:5]
	v_mfma_i32_16x16x64_i8 v[6:9], v[176:179], v[220:223], v[6:9]
	v_mfma_i32_16x16x64_i8 v[54:57], v[184:187], v[200:203], v[54:57]
	v_mfma_i32_16x16x64_i8 v[50:53], v[192:195], v[200:203], v[50:53]
	v_mfma_i32_16x16x64_i8 v[34:37], v[192:195], v[208:211], v[34:37]
	v_mfma_i32_16x16x64_i8 v[38:41], v[184:187], v[208:211], v[38:41]
	v_mfma_i32_16x16x64_i8 v[22:25], v[184:187], v[216:219], v[22:25]
	v_mfma_i32_16x16x64_i8 v[18:21], v[192:195], v[216:219], v[18:21]
	v_mfma_i32_16x16x64_i8 v[2:5], v[192:195], v[224:227], v[2:5]
	v_mfma_i32_16x16x64_i8 v[6:9], v[184:187], v[224:227], v[6:9]
	s_setprio 0
	s_barrier
	s_add_i32 s71, 0, 0x18000
	s_add_i32 s72, 0, 0x1c000
	v_add_u32_e32 v126, s71, v171
	v_add_u32_e32 v160, s72, v171
	ds_read_b128 v[106:109], v126
	ds_read_b128 v[110:113], v126 offset:1024
	ds_read_b128 v[122:125], v126 offset:2048
	ds_read_b128 v[126:129], v126 offset:3072
	ds_read_b128 v[176:179], v160
	ds_read_b128 v[184:187], v160 offset:1024
	ds_read_b128 v[188:191], v160 offset:2048
	ds_read_b128 v[192:195], v160 offset:3072
	s_add_u32 s36, s36, 0x80000
	s_addc_u32 s37, s37, 0
	s_mov_b32 m0, s41
	ds_read_b128 v[196:199], v175 offset:32768
	ds_read_b128 v[200:203], v175 offset:33792
	ds_read_b128 v[204:207], v175 offset:34816
	ds_read_b128 v[208:211], v175 offset:35840
	ds_read_b128 v[212:215], v175 offset:36864
	ds_read_b128 v[216:219], v175 offset:37888
	ds_read_b128 v[220:223], v175 offset:38912
	ds_read_b128 v[224:227], v175 offset:39936
	global_load_lds_dwordx4 v146, s[36:37]
	s_mov_b32 m0, s42
	s_nop 0
	global_load_lds_dwordx4 v148, s[36:37]
	s_waitcnt vmcnt(8)
	s_waitcnt lgkmcnt(0)
	s_barrier
	s_setprio 1
	s_waitcnt lgkmcnt(0)
	v_mfma_i32_16x16x64_i8 v[142:145], v[106:109], v[196:199], v[142:145]
	v_mfma_i32_16x16x64_i8 v[138:141], v[122:125], v[196:199], v[138:141]
	v_mfma_i32_16x16x64_i8 v[114:117], v[122:125], v[204:207], v[114:117]
	v_mfma_i32_16x16x64_i8 v[118:121], v[106:109], v[204:207], v[118:121]
	v_mfma_i32_16x16x64_i8 v[94:97], v[106:109], v[212:215], v[94:97]
	v_mfma_i32_16x16x64_i8 v[90:93], v[122:125], v[212:215], v[90:93]
	v_mfma_i32_16x16x64_i8 v[74:77], v[122:125], v[220:223], v[74:77]
	v_mfma_i32_16x16x64_i8 v[78:81], v[106:109], v[220:223], v[78:81]
	v_mfma_i32_16x16x64_i8 v[142:145], v[110:113], v[200:203], v[142:145]
	v_mfma_i32_16x16x64_i8 v[138:141], v[126:129], v[200:203], v[138:141]
	v_mfma_i32_16x16x64_i8 v[114:117], v[126:129], v[208:211], v[114:117]
	v_mfma_i32_16x16x64_i8 v[118:121], v[110:113], v[208:211], v[118:121]
	v_mfma_i32_16x16x64_i8 v[94:97], v[110:113], v[216:219], v[94:97]
	v_mfma_i32_16x16x64_i8 v[90:93], v[126:129], v[216:219], v[90:93]
	v_mfma_i32_16x16x64_i8 v[74:77], v[126:129], v[224:227], v[74:77]
	v_mfma_i32_16x16x64_i8 v[78:81], v[110:113], v[224:227], v[78:81]
	s_setprio 0
	s_setprio 1
	v_mfma_i32_16x16x64_i8 v[134:137], v[176:179], v[196:199], v[134:137]
	v_mfma_i32_16x16x64_i8 v[130:133], v[188:191], v[196:199], v[130:133]
	v_mfma_i32_16x16x64_i8 v[98:101], v[188:191], v[204:207], v[98:101]
	v_mfma_i32_16x16x64_i8 v[102:105], v[176:179], v[204:207], v[102:105]
	v_mfma_i32_16x16x64_i8 v[86:89], v[176:179], v[212:215], v[86:89]
	v_mfma_i32_16x16x64_i8 v[82:85], v[188:191], v[212:215], v[82:85]
	v_mfma_i32_16x16x64_i8 v[66:69], v[188:191], v[220:223], v[66:69]
	v_mfma_i32_16x16x64_i8 v[70:73], v[176:179], v[220:223], v[70:73]
	v_mfma_i32_16x16x64_i8 v[134:137], v[184:187], v[200:203], v[134:137]
	v_mfma_i32_16x16x64_i8 v[130:133], v[192:195], v[200:203], v[130:133]
	v_mfma_i32_16x16x64_i8 v[98:101], v[192:195], v[208:211], v[98:101]
	v_mfma_i32_16x16x64_i8 v[102:105], v[184:187], v[208:211], v[102:105]
	v_mfma_i32_16x16x64_i8 v[86:89], v[184:187], v[216:219], v[86:89]
	v_mfma_i32_16x16x64_i8 v[82:85], v[192:195], v[216:219], v[82:85]
	v_mfma_i32_16x16x64_i8 v[66:69], v[192:195], v[224:227], v[66:69]
	v_mfma_i32_16x16x64_i8 v[70:73], v[184:187], v[224:227], v[70:73]
	s_setprio 0
	s_barrier
	s_add_u32 s98, s36, 0xfff80080
	s_addc_u32 s99, s37, -1
	s_add_i32 s36, s71, s39
	s_mov_b32 m0, s36
	ds_read_b128 v[196:199], v175 offset:49152
	ds_read_b128 v[200:203], v175 offset:50176
	ds_read_b128 v[204:207], v175 offset:51200
	ds_read_b128 v[208:211], v175 offset:52224
	ds_read_b128 v[212:215], v175 offset:53248
	ds_read_b128 v[216:219], v175 offset:54272
	ds_read_b128 v[220:223], v175 offset:55296
	ds_read_b128 v[224:227], v175 offset:56320
	s_add_u32 s100, s34, 0x80
	s_addc_u32 s101, s35, 0
	global_load_lds_dwordx4 v146, s[100:101]
	s_add_i32 m0, s36, 0x2000
	s_add_u32 s34, s34, 0x80080
	s_addc_u32 s35, s35, 0
	s_add_i32 s36, s72, s39
	global_load_lds_dwordx4 v148, s[100:101]
	s_mov_b32 m0, s36
	s_nop 0
	global_load_lds_dwordx4 v146, s[34:35]
	s_add_i32 m0, s36, 0x2000
	s_nop 0
	global_load_lds_dwordx4 v148, s[34:35]
	s_mov_b32 m0, s46
	s_nop 0
	global_load_lds_dwordx4 v146, s[98:99]
	s_mov_b32 m0, s47
	s_nop 0
	global_load_lds_dwordx4 v148, s[98:99]
	s_waitcnt vmcnt(8)
	s_waitcnt lgkmcnt(0)
	s_barrier
	s_setprio 1
	s_waitcnt lgkmcnt(0)
	v_mfma_i32_16x16x64_i8 v[62:65], v[106:109], v[196:199], v[62:65]
	v_mfma_i32_16x16x64_i8 v[58:61], v[122:125], v[196:199], v[58:61]
	v_mfma_i32_16x16x64_i8 v[42:45], v[122:125], v[204:207], v[42:45]
	v_mfma_i32_16x16x64_i8 v[46:49], v[106:109], v[204:207], v[46:49]
	v_mfma_i32_16x16x64_i8 v[30:33], v[106:109], v[212:215], v[30:33]
	v_mfma_i32_16x16x64_i8 v[26:29], v[122:125], v[212:215], v[26:29]
	v_mfma_i32_16x16x64_i8 v[10:13], v[122:125], v[220:223], v[10:13]
	v_mfma_i32_16x16x64_i8 v[14:17], v[106:109], v[220:223], v[14:17]
	v_mfma_i32_16x16x64_i8 v[62:65], v[110:113], v[200:203], v[62:65]
	v_mfma_i32_16x16x64_i8 v[58:61], v[126:129], v[200:203], v[58:61]
	v_mfma_i32_16x16x64_i8 v[42:45], v[126:129], v[208:211], v[42:45]
	v_mfma_i32_16x16x64_i8 v[46:49], v[110:113], v[208:211], v[46:49]
	v_mfma_i32_16x16x64_i8 v[30:33], v[110:113], v[216:219], v[30:33]
	v_mfma_i32_16x16x64_i8 v[26:29], v[126:129], v[216:219], v[26:29]
	v_mfma_i32_16x16x64_i8 v[10:13], v[126:129], v[224:227], v[10:13]
	v_mfma_i32_16x16x64_i8 v[14:17], v[110:113], v[224:227], v[14:17]
	s_setprio 0
	s_setprio 1
	v_mfma_i32_16x16x64_i8 v[54:57], v[176:179], v[196:199], v[54:57]
	v_mfma_i32_16x16x64_i8 v[50:53], v[188:191], v[196:199], v[50:53]
	v_mfma_i32_16x16x64_i8 v[34:37], v[188:191], v[204:207], v[34:37]
	v_mfma_i32_16x16x64_i8 v[38:41], v[176:179], v[204:207], v[38:41]
	v_mfma_i32_16x16x64_i8 v[22:25], v[176:179], v[212:215], v[22:25]
	v_mfma_i32_16x16x64_i8 v[18:21], v[188:191], v[212:215], v[18:21]
	v_mfma_i32_16x16x64_i8 v[2:5], v[188:191], v[220:223], v[2:5]
	v_mfma_i32_16x16x64_i8 v[6:9], v[176:179], v[220:223], v[6:9]
	v_mfma_i32_16x16x64_i8 v[54:57], v[184:187], v[200:203], v[54:57]
	v_mfma_i32_16x16x64_i8 v[50:53], v[192:195], v[200:203], v[50:53]
	v_mfma_i32_16x16x64_i8 v[34:37], v[192:195], v[208:211], v[34:37]
	v_mfma_i32_16x16x64_i8 v[38:41], v[184:187], v[208:211], v[38:41]
	v_mfma_i32_16x16x64_i8 v[22:25], v[184:187], v[216:219], v[22:25]
	v_mfma_i32_16x16x64_i8 v[18:21], v[192:195], v[216:219], v[18:21]
	v_mfma_i32_16x16x64_i8 v[2:5], v[192:195], v[224:227], v[2:5]
	v_mfma_i32_16x16x64_i8 v[6:9], v[184:187], v[224:227], v[6:9]
	s_setprio 0
	s_barrier
	s_add_i32 s70, s70, 2
	s_add_u32 s30, s30, 0x100
	s_addc_u32 s31, s31, 0
	s_add_u32 s68, s68, 0x100
	s_addc_u32 s69, s69, 0
	s_cmp_gt_u32 s70, 29
	s_cbranch_scc0 .LBB0_848
	s_and_b64 vcc, exec, s[8:9]
	s_cbranch_vccz .LBB0_851
	s_barrier

.LBB0_863:
	ds_read_b128 v[158:161], v1
	ds_read_b128 v[162:165], v1 offset:1024
	ds_read_b128 v[166:169], v1 offset:2048
	ds_read_b128 v[170:173], v1 offset:3072
	ds_read_b128 v[174:177], v154
	ds_read_b128 v[178:181], v154 offset:1024
	ds_read_b128 v[184:187], v154 offset:2048
	ds_read_b128 v[188:191], v154 offset:3072
	s_add_u32 s12, s10, 0xfff00080
	s_addc_u32 s13, s11, -1
	s_add_u32 s37, s10, 0xf7f00080
	s_addc_u32 s38, s11, -1
	s_cmp_eq_u32 s36, 60
	s_cselect_b32 s15, s85, s13
	s_cselect_b32 s14, s81, s12
	s_cselect_b32 s13, s45, s38
	s_cselect_b32 s12, s44, s37
	s_mov_b32 m0, s24
	v_lshl_add_u64 v[224:225], s[10:11], 0, v[150:151]
	ds_read_b128 v[192:195], v155
	ds_read_b128 v[196:199], v155 offset:1024
	ds_read_b128 v[200:203], v155 offset:2048
	ds_read_b128 v[204:207], v155 offset:3072
	ds_read_b128 v[208:211], v155 offset:4096
	ds_read_b128 v[212:215], v155 offset:5120
	ds_read_b128 v[216:219], v155 offset:6144
	ds_read_b128 v[220:223], v155 offset:7168
	global_load_lds_dwordx4 v[224:225], off
	v_lshl_add_u64 v[224:225], s[10:11], 0, v[152:153]
	s_mov_b32 m0, s25
	s_nop 0
	global_load_lds_dwordx4 v[224:225], off
	s_waitcnt vmcnt(8)
	s_waitcnt lgkmcnt(0)
	s_barrier
	s_setprio 1
	s_waitcnt lgkmcnt(0)
	v_mfma_f32_16x16x32_bf16 v[126:129], v[158:161], v[192:195], v[126:129]
	v_mfma_f32_16x16x32_bf16 v[122:125], v[166:169], v[192:195], v[122:125]
	v_mfma_f32_16x16x32_bf16 v[106:109], v[166:169], v[200:203], v[106:109]
	v_mfma_f32_16x16x32_bf16 v[110:113], v[158:161], v[200:203], v[110:113]
	v_mfma_f32_16x16x32_bf16 v[94:97], v[158:161], v[208:211], v[94:97]
	v_mfma_f32_16x16x32_bf16 v[90:93], v[166:169], v[208:211], v[90:93]
	v_mfma_f32_16x16x32_bf16 v[74:77], v[166:169], v[216:219], v[74:77]
	v_mfma_f32_16x16x32_bf16 v[78:81], v[158:161], v[216:219], v[78:81]
	v_mfma_f32_16x16x32_bf16 v[126:129], v[162:165], v[196:199], v[126:129]
	v_mfma_f32_16x16x32_bf16 v[122:125], v[170:173], v[196:199], v[122:125]
	v_mfma_f32_16x16x32_bf16 v[106:109], v[170:173], v[204:207], v[106:109]
	v_mfma_f32_16x16x32_bf16 v[110:113], v[162:165], v[204:207], v[110:113]
	v_mfma_f32_16x16x32_bf16 v[94:97], v[162:165], v[212:215], v[94:97]
	v_mfma_f32_16x16x32_bf16 v[90:93], v[170:173], v[212:215], v[90:93]
	v_mfma_f32_16x16x32_bf16 v[74:77], v[170:173], v[220:223], v[74:77]
	v_mfma_f32_16x16x32_bf16 v[78:81], v[162:165], v[220:223], v[78:81]
	s_setprio 0
	s_setprio 1
	v_mfma_f32_16x16x32_bf16 v[118:121], v[174:177], v[192:195], v[118:121]
	v_mfma_f32_16x16x32_bf16 v[114:117], v[184:187], v[192:195], v[114:117]
	v_mfma_f32_16x16x32_bf16 v[98:101], v[184:187], v[200:203], v[98:101]
	v_mfma_f32_16x16x32_bf16 v[102:105], v[174:177], v[200:203], v[102:105]
	v_mfma_f32_16x16x32_bf16 v[86:89], v[174:177], v[208:211], v[86:89]
	v_mfma_f32_16x16x32_bf16 v[82:85], v[184:187], v[208:211], v[82:85]
	v_mfma_f32_16x16x32_bf16 v[66:69], v[184:187], v[216:219], v[66:69]
	v_mfma_f32_16x16x32_bf16 v[70:73], v[174:177], v[216:219], v[70:73]
	v_mfma_f32_16x16x32_bf16 v[118:121], v[178:181], v[196:199], v[118:121]
	v_mfma_f32_16x16x32_bf16 v[114:117], v[188:191], v[196:199], v[114:117]
	v_mfma_f32_16x16x32_bf16 v[98:101], v[188:191], v[204:207], v[98:101]
	v_mfma_f32_16x16x32_bf16 v[102:105], v[178:181], v[204:207], v[102:105]
	v_mfma_f32_16x16x32_bf16 v[86:89], v[178:181], v[212:215], v[86:89]
	v_mfma_f32_16x16x32_bf16 v[82:85], v[188:191], v[212:215], v[82:85]
	v_mfma_f32_16x16x32_bf16 v[66:69], v[188:191], v[220:223], v[66:69]
	v_mfma_f32_16x16x32_bf16 v[70:73], v[178:181], v[220:223], v[70:73]
	s_setprio 0
	s_barrier
	s_mov_b32 m0, s26
	v_lshl_add_u64 v[224:225], s[12:13], 0, v[130:131]
	s_add_u32 s38, s12, 0x100000
	ds_read_b128 v[192:195], v155 offset:16384
	ds_read_b128 v[196:199], v155 offset:17408
	ds_read_b128 v[200:203], v155 offset:18432
	ds_read_b128 v[204:207], v155 offset:19456
	ds_read_b128 v[208:211], v155 offset:20480
	ds_read_b128 v[212:215], v155 offset:21504
	ds_read_b128 v[216:219], v155 offset:22528
	ds_read_b128 v[220:223], v155 offset:23552
	global_load_lds_dwordx4 v[224:225], off
	v_lshl_add_u64 v[226:227], s[12:13], 0, v[132:133]
	s_mov_b32 m0, s27
	s_addc_u32 s39, s13, 0
	global_load_lds_dwordx4 v[226:227], off
	v_lshl_add_u64 v[228:229], s[38:39], 0, v[130:131]
	s_mov_b32 m0, s28
	v_lshl_add_u64 v[230:231], s[14:15], 0, v[132:133]
	global_load_lds_dwordx4 v[228:229], off
	v_lshl_add_u64 v[228:229], s[38:39], 0, v[132:133]
	s_mov_b32 m0, s29
	s_nop 0
	global_load_lds_dwordx4 v[228:229], off
	v_lshl_add_u64 v[228:229], s[14:15], 0, v[130:131]
	s_mov_b32 m0, s16
	s_nop 0
	global_load_lds_dwordx4 v[228:229], off
	s_mov_b32 m0, s17
	s_nop 0
	global_load_lds_dwordx4 v[230:231], off
	s_waitcnt vmcnt(8)
	s_waitcnt lgkmcnt(0)
	s_barrier
	s_setprio 1
	s_waitcnt lgkmcnt(0)
	v_mfma_f32_16x16x32_bf16 v[62:65], v[158:161], v[192:195], v[62:65]
	v_mfma_f32_16x16x32_bf16 v[58:61], v[166:169], v[192:195], v[58:61]
	v_mfma_f32_16x16x32_bf16 v[42:45], v[166:169], v[200:203], v[42:45]
	v_mfma_f32_16x16x32_bf16 v[46:49], v[158:161], v[200:203], v[46:49]
	v_mfma_f32_16x16x32_bf16 v[30:33], v[158:161], v[208:211], v[30:33]
	v_mfma_f32_16x16x32_bf16 v[26:29], v[166:169], v[208:211], v[26:29]
	v_mfma_f32_16x16x32_bf16 v[10:13], v[166:169], v[216:219], v[10:13]
	v_mfma_f32_16x16x32_bf16 v[14:17], v[158:161], v[216:219], v[14:17]
	v_mfma_f32_16x16x32_bf16 v[62:65], v[162:165], v[196:199], v[62:65]
	v_mfma_f32_16x16x32_bf16 v[58:61], v[170:173], v[196:199], v[58:61]
	v_mfma_f32_16x16x32_bf16 v[42:45], v[170:173], v[204:207], v[42:45]
	v_mfma_f32_16x16x32_bf16 v[46:49], v[162:165], v[204:207], v[46:49]
	v_mfma_f32_16x16x32_bf16 v[30:33], v[162:165], v[212:215], v[30:33]
	v_mfma_f32_16x16x32_bf16 v[26:29], v[170:173], v[212:215], v[26:29]
	v_mfma_f32_16x16x32_bf16 v[10:13], v[170:173], v[220:223], v[10:13]
	v_mfma_f32_16x16x32_bf16 v[14:17], v[162:165], v[220:223], v[14:17]
	s_setprio 0
	s_setprio 1
	v_mfma_f32_16x16x32_bf16 v[54:57], v[174:177], v[192:195], v[54:57]
	v_mfma_f32_16x16x32_bf16 v[50:53], v[184:187], v[192:195], v[50:53]
	v_mfma_f32_16x16x32_bf16 v[34:37], v[184:187], v[200:203], v[34:37]
	v_mfma_f32_16x16x32_bf16 v[38:41], v[174:177], v[200:203], v[38:41]
	v_mfma_f32_16x16x32_bf16 v[22:25], v[174:177], v[208:211], v[22:25]
	v_mfma_f32_16x16x32_bf16 v[18:21], v[184:187], v[208:211], v[18:21]
	v_mfma_f32_16x16x32_bf16 v[2:5], v[184:187], v[216:219], v[2:5]
	v_mfma_f32_16x16x32_bf16 v[6:9], v[174:177], v[216:219], v[6:9]
	v_mfma_f32_16x16x32_bf16 v[54:57], v[178:181], v[196:199], v[54:57]
	v_mfma_f32_16x16x32_bf16 v[50:53], v[188:191], v[196:199], v[50:53]
	v_mfma_f32_16x16x32_bf16 v[34:37], v[188:191], v[204:207], v[34:37]
	v_mfma_f32_16x16x32_bf16 v[38:41], v[178:181], v[204:207], v[38:41]
	v_mfma_f32_16x16x32_bf16 v[22:25], v[178:181], v[212:215], v[22:25]
	v_mfma_f32_16x16x32_bf16 v[18:21], v[188:191], v[212:215], v[18:21]
	v_mfma_f32_16x16x32_bf16 v[2:5], v[188:191], v[220:223], v[2:5]
	v_mfma_f32_16x16x32_bf16 v[6:9], v[178:181], v[220:223], v[6:9]
	s_setprio 0
	s_barrier
	ds_read_b128 v[158:161], v156
	ds_read_b128 v[162:165], v156 offset:1024
	ds_read_b128 v[166:169], v156 offset:2048
	ds_read_b128 v[170:173], v156 offset:3072
	ds_read_b128 v[174:177], v157
	ds_read_b128 v[178:181], v157 offset:1024
	ds_read_b128 v[184:187], v157 offset:2048
	ds_read_b128 v[188:191], v157 offset:3072
	s_add_u32 s14, s14, 0x100000
	s_addc_u32 s15, s15, 0
	s_mov_b32 m0, s18
	v_lshl_add_u64 v[232:233], s[14:15], 0, v[130:131]
	ds_read_b128 v[192:195], v155 offset:32768
	ds_read_b128 v[196:199], v155 offset:33792
	ds_read_b128 v[200:203], v155 offset:34816
	ds_read_b128 v[204:207], v155 offset:35840
	ds_read_b128 v[208:211], v155 offset:36864
	ds_read_b128 v[212:215], v155 offset:37888
	ds_read_b128 v[216:219], v155 offset:38912
	ds_read_b128 v[220:223], v155 offset:39936
	global_load_lds_dwordx4 v[232:233], off
	v_lshl_add_u64 v[232:233], s[14:15], 0, v[132:133]
	s_mov_b32 m0, s19
	s_nop 0
	global_load_lds_dwordx4 v[232:233], off
	s_waitcnt vmcnt(8)
	s_waitcnt lgkmcnt(0)
	s_barrier
	s_setprio 1
	s_waitcnt lgkmcnt(0)
	v_mfma_f32_16x16x32_bf16 v[126:129], v[158:161], v[192:195], v[126:129]
	v_mfma_f32_16x16x32_bf16 v[122:125], v[166:169], v[192:195], v[122:125]
	v_mfma_f32_16x16x32_bf16 v[106:109], v[166:169], v[200:203], v[106:109]
	v_mfma_f32_16x16x32_bf16 v[110:113], v[158:161], v[200:203], v[110:113]
	v_mfma_f32_16x16x32_bf16 v[94:97], v[158:161], v[208:211], v[94:97]
	v_mfma_f32_16x16x32_bf16 v[90:93], v[166:169], v[208:211], v[90:93]
	v_mfma_f32_16x16x32_bf16 v[74:77], v[166:169], v[216:219], v[74:77]
	v_mfma_f32_16x16x32_bf16 v[78:81], v[158:161], v[216:219], v[78:81]
	v_mfma_f32_16x16x32_bf16 v[126:129], v[162:165], v[196:199], v[126:129]
	v_mfma_f32_16x16x32_bf16 v[122:125], v[170:173], v[196:199], v[122:125]
	v_mfma_f32_16x16x32_bf16 v[106:109], v[170:173], v[204:207], v[106:109]
	v_mfma_f32_16x16x32_bf16 v[110:113], v[162:165], v[204:207], v[110:113]
	v_mfma_f32_16x16x32_bf16 v[94:97], v[162:165], v[212:215], v[94:97]
	v_mfma_f32_16x16x32_bf16 v[90:93], v[170:173], v[212:215], v[90:93]
	v_mfma_f32_16x16x32_bf16 v[74:77], v[170:173], v[220:223], v[74:77]
	v_mfma_f32_16x16x32_bf16 v[78:81], v[162:165], v[220:223], v[78:81]
	s_setprio 0
	s_setprio 1
	v_mfma_f32_16x16x32_bf16 v[118:121], v[174:177], v[192:195], v[118:121]
	v_mfma_f32_16x16x32_bf16 v[114:117], v[184:187], v[192:195], v[114:117]
	v_mfma_f32_16x16x32_bf16 v[98:101], v[184:187], v[200:203], v[98:101]
	v_mfma_f32_16x16x32_bf16 v[102:105], v[174:177], v[200:203], v[102:105]
	v_mfma_f32_16x16x32_bf16 v[86:89], v[174:177], v[208:211], v[86:89]
	v_mfma_f32_16x16x32_bf16 v[82:85], v[184:187], v[208:211], v[82:85]
	v_mfma_f32_16x16x32_bf16 v[66:69], v[184:187], v[216:219], v[66:69]
	v_mfma_f32_16x16x32_bf16 v[70:73], v[174:177], v[216:219], v[70:73]
	v_mfma_f32_16x16x32_bf16 v[118:121], v[178:181], v[196:199], v[118:121]
	v_mfma_f32_16x16x32_bf16 v[114:117], v[188:191], v[196:199], v[114:117]
	v_mfma_f32_16x16x32_bf16 v[98:101], v[188:191], v[204:207], v[98:101]
	v_mfma_f32_16x16x32_bf16 v[102:105], v[178:181], v[204:207], v[102:105]
	v_mfma_f32_16x16x32_bf16 v[86:89], v[178:181], v[212:215], v[86:89]
	v_mfma_f32_16x16x32_bf16 v[82:85], v[188:191], v[212:215], v[82:85]
	v_mfma_f32_16x16x32_bf16 v[66:69], v[188:191], v[220:223], v[66:69]
	v_mfma_f32_16x16x32_bf16 v[70:73], v[178:181], v[220:223], v[70:73]
	s_setprio 0
	s_barrier
	s_mov_b32 m0, s30
	v_lshl_add_u64 v[224:225], v[224:225], 0, s[8:9]
	s_add_u32 s12, s12, 0x100080
	ds_read_b128 v[192:195], v155 offset:49152
	ds_read_b128 v[196:199], v155 offset:50176
	ds_read_b128 v[200:203], v155 offset:51200
	ds_read_b128 v[204:207], v155 offset:52224
	ds_read_b128 v[208:211], v155 offset:53248
	ds_read_b128 v[212:215], v155 offset:54272
	ds_read_b128 v[216:219], v155 offset:55296
	ds_read_b128 v[220:223], v155 offset:56320
	global_load_lds_dwordx4 v[224:225], off
	v_lshl_add_u64 v[224:225], v[226:227], 0, s[8:9]
	s_mov_b32 m0, s31
	s_addc_u32 s13, s13, 0
	global_load_lds_dwordx4 v[224:225], off
	v_lshl_add_u64 v[224:225], s[12:13], 0, v[130:131]
	s_mov_b32 m0, s34
	s_nop 0
	global_load_lds_dwordx4 v[224:225], off
	v_lshl_add_u64 v[224:225], s[12:13], 0, v[132:133]
	s_mov_b32 m0, s35
	s_nop 0
	global_load_lds_dwordx4 v[224:225], off
	v_lshl_add_u64 v[224:225], v[228:229], 0, s[8:9]
	s_mov_b32 m0, s21
	s_nop 0
	global_load_lds_dwordx4 v[224:225], off
	v_lshl_add_u64 v[224:225], v[230:231], 0, s[8:9]
	s_mov_b32 m0, s22
	s_nop 0
	global_load_lds_dwordx4 v[224:225], off
	s_waitcnt vmcnt(8)
	s_waitcnt lgkmcnt(0)
	s_barrier
	s_setprio 1
	s_waitcnt lgkmcnt(0)
	v_mfma_f32_16x16x32_bf16 v[62:65], v[158:161], v[192:195], v[62:65]
	v_mfma_f32_16x16x32_bf16 v[58:61], v[166:169], v[192:195], v[58:61]
	v_mfma_f32_16x16x32_bf16 v[42:45], v[166:169], v[200:203], v[42:45]
	v_mfma_f32_16x16x32_bf16 v[46:49], v[158:161], v[200:203], v[46:49]
	v_mfma_f32_16x16x32_bf16 v[30:33], v[158:161], v[208:211], v[30:33]
	v_mfma_f32_16x16x32_bf16 v[26:29], v[166:169], v[208:211], v[26:29]
	v_mfma_f32_16x16x32_bf16 v[10:13], v[166:169], v[216:219], v[10:13]
	v_mfma_f32_16x16x32_bf16 v[14:17], v[158:161], v[216:219], v[14:17]
	v_mfma_f32_16x16x32_bf16 v[62:65], v[162:165], v[196:199], v[62:65]
	v_mfma_f32_16x16x32_bf16 v[58:61], v[170:173], v[196:199], v[58:61]
	v_mfma_f32_16x16x32_bf16 v[42:45], v[170:173], v[204:207], v[42:45]
	v_mfma_f32_16x16x32_bf16 v[46:49], v[162:165], v[204:207], v[46:49]
	v_mfma_f32_16x16x32_bf16 v[30:33], v[162:165], v[212:215], v[30:33]
	v_mfma_f32_16x16x32_bf16 v[26:29], v[170:173], v[212:215], v[26:29]
	v_mfma_f32_16x16x32_bf16 v[10:13], v[170:173], v[220:223], v[10:13]
	v_mfma_f32_16x16x32_bf16 v[14:17], v[162:165], v[220:223], v[14:17]
	s_setprio 0
	s_setprio 1
	v_mfma_f32_16x16x32_bf16 v[54:57], v[174:177], v[192:195], v[54:57]
	v_mfma_f32_16x16x32_bf16 v[50:53], v[184:187], v[192:195], v[50:53]
	v_mfma_f32_16x16x32_bf16 v[34:37], v[184:187], v[200:203], v[34:37]
	v_mfma_f32_16x16x32_bf16 v[38:41], v[174:177], v[200:203], v[38:41]
	v_mfma_f32_16x16x32_bf16 v[22:25], v[174:177], v[208:211], v[22:25]
	v_mfma_f32_16x16x32_bf16 v[18:21], v[184:187], v[208:211], v[18:21]
	v_mfma_f32_16x16x32_bf16 v[2:5], v[184:187], v[216:219], v[2:5]
	v_mfma_f32_16x16x32_bf16 v[6:9], v[174:177], v[216:219], v[6:9]
	v_mfma_f32_16x16x32_bf16 v[54:57], v[178:181], v[196:199], v[54:57]
	v_mfma_f32_16x16x32_bf16 v[50:53], v[188:191], v[196:199], v[50:53]
	v_mfma_f32_16x16x32_bf16 v[34:37], v[188:191], v[204:207], v[34:37]
	v_mfma_f32_16x16x32_bf16 v[38:41], v[178:181], v[204:207], v[38:41]
	v_mfma_f32_16x16x32_bf16 v[22:25], v[178:181], v[212:215], v[22:25]
	v_mfma_f32_16x16x32_bf16 v[18:21], v[188:191], v[212:215], v[18:21]
	v_mfma_f32_16x16x32_bf16 v[2:5], v[188:191], v[220:223], v[2:5]
	v_mfma_f32_16x16x32_bf16 v[6:9], v[178:181], v[220:223], v[6:9]
	s_setprio 0
	s_barrier
	s_add_i32 s36, s36, 2
	s_add_u32 s10, s10, 0x100
	s_addc_u32 s11, s11, 0
	s_cmp_gt_u32 s36, 61
	s_cbranch_scc0 .LBB0_863
	s_and_b64 vcc, exec, s[2:3]
	s_cbranch_vccz .LBB0_866
	s_barrier

.LBB0_937:
	ds_read_b128 v[128:131], v159
	ds_read_b128 v[132:135], v159 offset:1024
	ds_read_b128 v[136:139], v159 offset:2048
	ds_read_b128 v[140:143], v159 offset:3072
	ds_read_b128 v[162:165], v160
	ds_read_b128 v[166:169], v160 offset:1024
	ds_read_b128 v[170:173], v160 offset:2048
	ds_read_b128 v[174:177], v160 offset:3072
	s_add_u32 s30, s28, 0xffc00080
	s_addc_u32 s31, s29, -1
	s_cmpk_eq_i32 s70, 0xfc
	s_cselect_b32 s35, s21, s31
	s_cselect_b32 s34, s66, s30
	s_cselect_b32 s31, s19, s69
	s_cselect_b32 s30, s67, s68
	s_add_i32 m0, s27, 0xc000
	ds_read_b128 v[178:181], v161
	ds_read_b128 v[184:187], v161 offset:1024
	ds_read_b128 v[188:191], v161 offset:2048
	ds_read_b128 v[192:195], v161 offset:3072
	ds_read_b128 v[196:199], v161 offset:4096
	ds_read_b128 v[200:203], v161 offset:5120
	ds_read_b128 v[204:207], v161 offset:6144
	ds_read_b128 v[208:211], v161 offset:7168
	global_load_lds_dwordx4 v148, s[28:29]
	s_add_i32 m0, s27, 0xe000
	s_nop 0
	global_load_lds_dwordx4 v150, s[28:29]
	s_waitcnt vmcnt(8)
	s_waitcnt lgkmcnt(0)
	s_barrier
	s_setprio 1
	s_waitcnt lgkmcnt(0)
	v_mfma_f32_16x16x32_bf16 v[124:127], v[128:131], v[178:181], v[124:127]
	v_mfma_f32_16x16x32_bf16 v[120:123], v[136:139], v[178:181], v[120:123]
	v_mfma_f32_16x16x32_bf16 v[112:115], v[136:139], v[188:191], v[112:115]
	v_mfma_f32_16x16x32_bf16 v[116:119], v[128:131], v[188:191], v[116:119]
	v_mfma_f32_16x16x32_bf16 v[108:111], v[128:131], v[196:199], v[108:111]
	v_mfma_f32_16x16x32_bf16 v[100:103], v[136:139], v[196:199], v[100:103]
	v_mfma_f32_16x16x32_bf16 v[72:75], v[136:139], v[204:207], v[72:75]
	v_mfma_f32_16x16x32_bf16 v[76:79], v[128:131], v[204:207], v[76:79]
	v_mfma_f32_16x16x32_bf16 v[124:127], v[132:135], v[184:187], v[124:127]
	v_mfma_f32_16x16x32_bf16 v[120:123], v[140:143], v[184:187], v[120:123]
	v_mfma_f32_16x16x32_bf16 v[112:115], v[140:143], v[192:195], v[112:115]
	v_mfma_f32_16x16x32_bf16 v[116:119], v[132:135], v[192:195], v[116:119]
	v_mfma_f32_16x16x32_bf16 v[108:111], v[132:135], v[200:203], v[108:111]
	v_mfma_f32_16x16x32_bf16 v[100:103], v[140:143], v[200:203], v[100:103]
	v_mfma_f32_16x16x32_bf16 v[72:75], v[140:143], v[208:211], v[72:75]
	v_mfma_f32_16x16x32_bf16 v[76:79], v[132:135], v[208:211], v[76:79]
	s_setprio 0
	s_setprio 1
	v_mfma_f32_16x16x32_bf16 v[104:107], v[162:165], v[178:181], v[104:107]
	v_mfma_f32_16x16x32_bf16 v[96:99], v[170:173], v[178:181], v[96:99]
	v_mfma_f32_16x16x32_bf16 v[88:91], v[170:173], v[188:191], v[88:91]
	v_mfma_f32_16x16x32_bf16 v[92:95], v[162:165], v[188:191], v[92:95]
	v_mfma_f32_16x16x32_bf16 v[84:87], v[162:165], v[196:199], v[84:87]
	v_mfma_f32_16x16x32_bf16 v[80:83], v[170:173], v[196:199], v[80:83]
	v_mfma_f32_16x16x32_bf16 v[64:67], v[170:173], v[204:207], v[64:67]
	v_mfma_f32_16x16x32_bf16 v[68:71], v[162:165], v[204:207], v[68:71]
	v_mfma_f32_16x16x32_bf16 v[104:107], v[166:169], v[184:187], v[104:107]
	v_mfma_f32_16x16x32_bf16 v[96:99], v[174:177], v[184:187], v[96:99]
	v_mfma_f32_16x16x32_bf16 v[88:91], v[174:177], v[192:195], v[88:91]
	v_mfma_f32_16x16x32_bf16 v[92:95], v[166:169], v[192:195], v[92:95]
	v_mfma_f32_16x16x32_bf16 v[84:87], v[166:169], v[200:203], v[84:87]
	v_mfma_f32_16x16x32_bf16 v[80:83], v[174:177], v[200:203], v[80:83]
	v_mfma_f32_16x16x32_bf16 v[64:67], v[174:177], v[208:211], v[64:67]
	v_mfma_f32_16x16x32_bf16 v[68:71], v[166:169], v[208:211], v[68:71]
	s_setprio 0
	s_barrier
	s_add_i32 s71, s51, s36
	s_mov_b32 m0, s71
	ds_read_b128 v[178:181], v161 offset:16384
	ds_read_b128 v[184:187], v161 offset:17408
	ds_read_b128 v[188:191], v161 offset:18432
	ds_read_b128 v[192:195], v161 offset:19456
	ds_read_b128 v[196:199], v161 offset:20480
	ds_read_b128 v[200:203], v161 offset:21504
	ds_read_b128 v[204:207], v161 offset:22528
	ds_read_b128 v[208:211], v161 offset:23552
	global_load_lds_dwordx4 v144, s[30:31]
	s_add_i32 m0, s71, 0x2000
	s_add_u32 s72, s30, 0x400000
	s_addc_u32 s73, s31, 0
	s_add_i32 s71, s52, s36
	global_load_lds_dwordx4 v146, s[30:31]
	s_mov_b32 m0, s71
	s_nop 0
	global_load_lds_dwordx4 v144, s[72:73]
	s_add_i32 m0, s71, 0x2000
	s_nop 0
	global_load_lds_dwordx4 v146, s[72:73]
	s_mov_b32 m0, s27
	s_nop 0
	global_load_lds_dwordx4 v144, s[34:35]
	s_mov_b32 m0, s38
	s_nop 0
	global_load_lds_dwordx4 v146, s[34:35]
	s_waitcnt vmcnt(8)
	s_waitcnt lgkmcnt(0)
	s_barrier
	s_setprio 1
	s_waitcnt lgkmcnt(0)
	v_mfma_f32_16x16x32_bf16 v[60:63], v[128:131], v[178:181], v[60:63]
	v_mfma_f32_16x16x32_bf16 v[56:59], v[136:139], v[178:181], v[56:59]
	v_mfma_f32_16x16x32_bf16 v[44:47], v[136:139], v[188:191], v[44:47]
	v_mfma_f32_16x16x32_bf16 v[52:55], v[128:131], v[188:191], v[52:55]
	v_mfma_f32_16x16x32_bf16 v[36:39], v[128:131], v[196:199], v[36:39]
	v_mfma_f32_16x16x32_bf16 v[28:31], v[136:139], v[196:199], v[28:31]
	v_mfma_f32_16x16x32_bf16 v[12:15], v[136:139], v[204:207], v[12:15]
	v_mfma_f32_16x16x32_bf16 v[20:23], v[128:131], v[204:207], v[20:23]
	v_mfma_f32_16x16x32_bf16 v[60:63], v[132:135], v[184:187], v[60:63]
	v_mfma_f32_16x16x32_bf16 v[56:59], v[140:143], v[184:187], v[56:59]
	v_mfma_f32_16x16x32_bf16 v[44:47], v[140:143], v[192:195], v[44:47]
	v_mfma_f32_16x16x32_bf16 v[52:55], v[132:135], v[192:195], v[52:55]
	v_mfma_f32_16x16x32_bf16 v[36:39], v[132:135], v[200:203], v[36:39]
	v_mfma_f32_16x16x32_bf16 v[28:31], v[140:143], v[200:203], v[28:31]
	v_mfma_f32_16x16x32_bf16 v[12:15], v[140:143], v[208:211], v[12:15]
	v_mfma_f32_16x16x32_bf16 v[20:23], v[132:135], v[208:211], v[20:23]
	s_setprio 0
	s_setprio 1
	v_mfma_f32_16x16x32_bf16 v[48:51], v[162:165], v[178:181], v[48:51]
	v_mfma_f32_16x16x32_bf16 v[40:43], v[170:173], v[178:181], v[40:43]
	v_mfma_f32_16x16x32_bf16 v[24:27], v[170:173], v[188:191], v[24:27]
	v_mfma_f32_16x16x32_bf16 v[32:35], v[162:165], v[188:191], v[32:35]
	v_mfma_f32_16x16x32_bf16 v[16:19], v[162:165], v[196:199], v[16:19]
	v_mfma_f32_16x16x32_bf16 v[8:11], v[170:173], v[196:199], v[8:11]
	v_mfma_f32_16x16x32_bf16 v[0:3], v[170:173], v[204:207], v[0:3]
	v_mfma_f32_16x16x32_bf16 v[4:7], v[162:165], v[204:207], v[4:7]
	v_mfma_f32_16x16x32_bf16 v[48:51], v[166:169], v[184:187], v[48:51]
	v_mfma_f32_16x16x32_bf16 v[40:43], v[174:177], v[184:187], v[40:43]
	v_mfma_f32_16x16x32_bf16 v[24:27], v[174:177], v[192:195], v[24:27]
	v_mfma_f32_16x16x32_bf16 v[32:35], v[166:169], v[192:195], v[32:35]
	v_mfma_f32_16x16x32_bf16 v[16:19], v[166:169], v[200:203], v[16:19]
	v_mfma_f32_16x16x32_bf16 v[8:11], v[174:177], v[200:203], v[8:11]
	v_mfma_f32_16x16x32_bf16 v[0:3], v[174:177], v[208:211], v[0:3]
	v_mfma_f32_16x16x32_bf16 v[4:7], v[166:169], v[208:211], v[4:7]
	s_setprio 0
	s_barrier
	s_add_i32 s71, 0, 0x18000
	s_add_i32 s72, 0, 0x1c000
	v_add_u32_e32 v140, s71, v157
	v_add_u32_e32 v174, s72, v157
	ds_read_b128 v[128:131], v140
	ds_read_b128 v[132:135], v140 offset:1024
	ds_read_b128 v[136:139], v140 offset:2048
	ds_read_b128 v[140:143], v140 offset:3072
	ds_read_b128 v[162:165], v174
	ds_read_b128 v[166:169], v174 offset:1024
	ds_read_b128 v[170:173], v174 offset:2048
	ds_read_b128 v[174:177], v174 offset:3072
	s_add_u32 s34, s34, 0x400000
	s_addc_u32 s35, s35, 0
	s_mov_b32 m0, s39
	ds_read_b128 v[178:181], v161 offset:32768
	ds_read_b128 v[184:187], v161 offset:33792
	ds_read_b128 v[188:191], v161 offset:34816
	ds_read_b128 v[192:195], v161 offset:35840
	ds_read_b128 v[196:199], v161 offset:36864
	ds_read_b128 v[200:203], v161 offset:37888
	ds_read_b128 v[204:207], v161 offset:38912
	ds_read_b128 v[208:211], v161 offset:39936
	global_load_lds_dwordx4 v144, s[34:35]
	s_mov_b32 m0, s40
	s_nop 0
	global_load_lds_dwordx4 v146, s[34:35]
	s_waitcnt vmcnt(8)
	s_waitcnt lgkmcnt(0)
	s_barrier
	s_setprio 1
	s_waitcnt lgkmcnt(0)
	v_mfma_f32_16x16x32_bf16 v[124:127], v[128:131], v[178:181], v[124:127]
	v_mfma_f32_16x16x32_bf16 v[120:123], v[136:139], v[178:181], v[120:123]
	v_mfma_f32_16x16x32_bf16 v[112:115], v[136:139], v[188:191], v[112:115]
	v_mfma_f32_16x16x32_bf16 v[116:119], v[128:131], v[188:191], v[116:119]
	v_mfma_f32_16x16x32_bf16 v[108:111], v[128:131], v[196:199], v[108:111]
	v_mfma_f32_16x16x32_bf16 v[100:103], v[136:139], v[196:199], v[100:103]
	v_mfma_f32_16x16x32_bf16 v[72:75], v[136:139], v[204:207], v[72:75]
	v_mfma_f32_16x16x32_bf16 v[76:79], v[128:131], v[204:207], v[76:79]
	v_mfma_f32_16x16x32_bf16 v[124:127], v[132:135], v[184:187], v[124:127]
	v_mfma_f32_16x16x32_bf16 v[120:123], v[140:143], v[184:187], v[120:123]
	v_mfma_f32_16x16x32_bf16 v[112:115], v[140:143], v[192:195], v[112:115]
	v_mfma_f32_16x16x32_bf16 v[116:119], v[132:135], v[192:195], v[116:119]
	v_mfma_f32_16x16x32_bf16 v[108:111], v[132:135], v[200:203], v[108:111]
	v_mfma_f32_16x16x32_bf16 v[100:103], v[140:143], v[200:203], v[100:103]
	v_mfma_f32_16x16x32_bf16 v[72:75], v[140:143], v[208:211], v[72:75]
	v_mfma_f32_16x16x32_bf16 v[76:79], v[132:135], v[208:211], v[76:79]
	s_setprio 0
	s_setprio 1
	v_mfma_f32_16x16x32_bf16 v[104:107], v[162:165], v[178:181], v[104:107]
	v_mfma_f32_16x16x32_bf16 v[96:99], v[170:173], v[178:181], v[96:99]
	v_mfma_f32_16x16x32_bf16 v[88:91], v[170:173], v[188:191], v[88:91]
	v_mfma_f32_16x16x32_bf16 v[92:95], v[162:165], v[188:191], v[92:95]
	v_mfma_f32_16x16x32_bf16 v[84:87], v[162:165], v[196:199], v[84:87]
	v_mfma_f32_16x16x32_bf16 v[80:83], v[170:173], v[196:199], v[80:83]
	v_mfma_f32_16x16x32_bf16 v[64:67], v[170:173], v[204:207], v[64:67]
	v_mfma_f32_16x16x32_bf16 v[68:71], v[162:165], v[204:207], v[68:71]
	v_mfma_f32_16x16x32_bf16 v[104:107], v[166:169], v[184:187], v[104:107]
	v_mfma_f32_16x16x32_bf16 v[96:99], v[174:177], v[184:187], v[96:99]
	v_mfma_f32_16x16x32_bf16 v[88:91], v[174:177], v[192:195], v[88:91]
	v_mfma_f32_16x16x32_bf16 v[92:95], v[166:169], v[192:195], v[92:95]
	v_mfma_f32_16x16x32_bf16 v[84:87], v[166:169], v[200:203], v[84:87]
	v_mfma_f32_16x16x32_bf16 v[80:83], v[174:177], v[200:203], v[80:83]
	v_mfma_f32_16x16x32_bf16 v[64:67], v[174:177], v[208:211], v[64:67]
	v_mfma_f32_16x16x32_bf16 v[68:71], v[166:169], v[208:211], v[68:71]
	s_setprio 0
	s_barrier
	s_add_u32 s98, s34, 0xffc00080
	s_addc_u32 s99, s35, -1
	s_add_i32 s34, s71, s36
	s_mov_b32 m0, s34
	ds_read_b128 v[178:181], v161 offset:49152
	ds_read_b128 v[184:187], v161 offset:50176
	ds_read_b128 v[188:191], v161 offset:51200
	ds_read_b128 v[192:195], v161 offset:52224
	ds_read_b128 v[196:199], v161 offset:53248
	ds_read_b128 v[200:203], v161 offset:54272
	ds_read_b128 v[204:207], v161 offset:55296
	ds_read_b128 v[208:211], v161 offset:56320
	s_add_u32 s100, s30, 0x80
	s_addc_u32 s101, s31, 0
	global_load_lds_dwordx4 v144, s[100:101]
	s_add_i32 m0, s34, 0x2000
	s_add_u32 s30, s30, 0x400080
	s_addc_u32 s31, s31, 0
	s_add_i32 s34, s72, s36
	global_load_lds_dwordx4 v146, s[100:101]
	s_mov_b32 m0, s34
	s_nop 0
	global_load_lds_dwordx4 v144, s[30:31]
	s_add_i32 m0, s34, 0x2000
	s_nop 0
	global_load_lds_dwordx4 v146, s[30:31]
	s_mov_b32 m0, s47
	s_nop 0
	global_load_lds_dwordx4 v144, s[98:99]
	s_mov_b32 m0, s50
	s_nop 0
	global_load_lds_dwordx4 v146, s[98:99]
	s_waitcnt vmcnt(8)
	s_waitcnt lgkmcnt(0)
	s_barrier
	s_setprio 1
	s_waitcnt lgkmcnt(0)
	v_mfma_f32_16x16x32_bf16 v[60:63], v[128:131], v[178:181], v[60:63]
	v_mfma_f32_16x16x32_bf16 v[56:59], v[136:139], v[178:181], v[56:59]
	v_mfma_f32_16x16x32_bf16 v[44:47], v[136:139], v[188:191], v[44:47]
	v_mfma_f32_16x16x32_bf16 v[52:55], v[128:131], v[188:191], v[52:55]
	v_mfma_f32_16x16x32_bf16 v[36:39], v[128:131], v[196:199], v[36:39]
	v_mfma_f32_16x16x32_bf16 v[28:31], v[136:139], v[196:199], v[28:31]
	v_mfma_f32_16x16x32_bf16 v[12:15], v[136:139], v[204:207], v[12:15]
	v_mfma_f32_16x16x32_bf16 v[20:23], v[128:131], v[204:207], v[20:23]
	v_mfma_f32_16x16x32_bf16 v[60:63], v[132:135], v[184:187], v[60:63]
	v_mfma_f32_16x16x32_bf16 v[56:59], v[140:143], v[184:187], v[56:59]
	v_mfma_f32_16x16x32_bf16 v[44:47], v[140:143], v[192:195], v[44:47]
	v_mfma_f32_16x16x32_bf16 v[52:55], v[132:135], v[192:195], v[52:55]
	v_mfma_f32_16x16x32_bf16 v[36:39], v[132:135], v[200:203], v[36:39]
	v_mfma_f32_16x16x32_bf16 v[28:31], v[140:143], v[200:203], v[28:31]
	v_mfma_f32_16x16x32_bf16 v[12:15], v[140:143], v[208:211], v[12:15]
	v_mfma_f32_16x16x32_bf16 v[20:23], v[132:135], v[208:211], v[20:23]
	s_setprio 0
	s_setprio 1
	v_mfma_f32_16x16x32_bf16 v[48:51], v[162:165], v[178:181], v[48:51]
	v_mfma_f32_16x16x32_bf16 v[40:43], v[170:173], v[178:181], v[40:43]
	v_mfma_f32_16x16x32_bf16 v[24:27], v[170:173], v[188:191], v[24:27]
	v_mfma_f32_16x16x32_bf16 v[32:35], v[162:165], v[188:191], v[32:35]
	v_mfma_f32_16x16x32_bf16 v[16:19], v[162:165], v[196:199], v[16:19]
	v_mfma_f32_16x16x32_bf16 v[8:11], v[170:173], v[196:199], v[8:11]
	v_mfma_f32_16x16x32_bf16 v[0:3], v[170:173], v[204:207], v[0:3]
	v_mfma_f32_16x16x32_bf16 v[4:7], v[162:165], v[204:207], v[4:7]
	v_mfma_f32_16x16x32_bf16 v[48:51], v[166:169], v[184:187], v[48:51]
	v_mfma_f32_16x16x32_bf16 v[40:43], v[174:177], v[184:187], v[40:43]
	v_mfma_f32_16x16x32_bf16 v[24:27], v[174:177], v[192:195], v[24:27]
	v_mfma_f32_16x16x32_bf16 v[32:35], v[166:169], v[192:195], v[32:35]
	v_mfma_f32_16x16x32_bf16 v[16:19], v[166:169], v[200:203], v[16:19]
	v_mfma_f32_16x16x32_bf16 v[8:11], v[174:177], v[200:203], v[8:11]
	v_mfma_f32_16x16x32_bf16 v[0:3], v[174:177], v[208:211], v[0:3]
	v_mfma_f32_16x16x32_bf16 v[4:7], v[166:169], v[208:211], v[4:7]
	s_setprio 0
	s_barrier
	s_add_i32 s70, s70, 2
	s_add_u32 s28, s28, 0x100
	s_addc_u32 s29, s29, 0
	s_add_u32 s68, s68, 0x100
	s_addc_u32 s69, s69, 0
	s_cmpk_gt_u32 s70, 0xfd
	s_cbranch_scc0 .LBB0_937
	s_and_b64 vcc, exec, s[8:9]
	s_cbranch_vccz .LBB0_940
	s_barrier
